# ctx attention unit prologue tiles by LDS-DMA, FFT stage-0 second row batch loaded together with the first, attention first K reads issued before the DMA pieces
# speedup vs baseline: 1.0162x; 1.0002x over previous
.LBB0_803:
	s_lshl_b32 s0, s4, 11
	s_and_b32 s7, s4, 31
	v_mov_b32_e32 v78, v0
	s_and_b32 s0, s0, 0x3800
	v_readlane_b32 s1, v252, 2
	s_add_u32 s0, s1, s0
	v_and_b32_e32 v80, 15, v78
	v_readlane_b32 s1, v252, 3
	s_addc_u32 s1, s1, 0
	v_lshlrev_b32_e32 v98, 7, v80
	s_waitcnt lgkmcnt(0)
	v_lshl_add_u64 v[2:3], s[0:1], 0, v[98:99]
	v_readlane_b32 s0, v251, 62
	v_lshlrev_b32_e32 v10, 4, v80
	v_mov_b32_e32 v11, v99
	v_readlane_b32 s1, v251, 63
	v_readlane_b32 s10, v254, 15
	v_ashrrev_i32_e32 v17, 4, v78
	v_bfe_u32 v81, v78, 4, 2
	v_lshl_add_u64 v[14:15], s[0:1], 0, v[10:11]
	v_add_u32_e32 v16, s10, v10
	v_lshlrev_b32_e32 v10, 7, v17
	v_lshlrev_b32_e32 v74, 4, v81
	v_mov_b32_e32 v75, v99
	v_ashrrev_i32_e32 v11, 31, v10
	v_lshl_add_u64 v[2:3], v[2:3], 0, v[74:75]
	v_lshl_add_u64 v[10:11], v[10:11], 1, v[14:15]
	global_load_dwordx4 v[6:9], v[2:3], off
	s_nop 0
	global_load_dwordx4 v[2:5], v[2:3], off offset:64
	v_mul_lo_u32 v17, v17, s31
	global_load_dwordx4 v[100:103], v[10:11], off
	v_add_u32_e32 v18, v16, v17
	v_add_u32_e32 v20, 0x200, v78
	v_readlane_b32 s11, v254, 16
	v_ashrrev_i32_e32 v82, 6, v78
	v_readlane_b32 s8, v252, 0
	v_readlane_b32 s9, v252, 1
	v_lshrrev_b32_e32 v83, 4, v78
	v_lshlrev_b32_e32 v79, 6, v80
	v_mov_b32_e32 v124, v18
	v_ashrrev_i32_e32 v18, 4, v20
	v_lshlrev_b32_e32 v10, 7, v18
	v_ashrrev_i32_e32 v11, 31, v10
	v_lshl_add_u64 v[10:11], v[10:11], 1, v[14:15]
	global_load_dwordx4 v[104:107], v[10:11], off
	v_mul_lo_u32 v21, v18, s31
	v_add_u32_e32 v18, v16, v21
	v_mov_b32_e32 v125, v18
	v_add_u32_e32 v10, 0x400, v78
	v_ashrrev_i32_e32 v18, 4, v10
	v_lshlrev_b32_e32 v10, 7, v18
	v_ashrrev_i32_e32 v11, 31, v10
	v_lshl_add_u64 v[10:11], v[10:11], 1, v[14:15]
	global_load_dwordx4 v[108:111], v[10:11], off
	v_mad_u64_u32 v[18:19], s[0:1], v18, s31, v[16:17]
	v_mov_b32_e32 v126, v18
	v_add_u32_e32 v10, 0x600, v78
	v_ashrrev_i32_e32 v18, 4, v10
	v_lshlrev_b32_e32 v10, 7, v18
	v_ashrrev_i32_e32 v11, 31, v10
	v_lshl_add_u64 v[10:11], v[10:11], 1, v[14:15]
	global_load_dwordx4 v[112:115], v[10:11], off
	v_mad_u64_u32 v[14:15], s[0:1], v18, s31, v[16:17]
	v_readlane_b32 s0, v252, 4
	v_readlane_b32 s1, v252, 5
	v_mov_b32_e32 v127, v14
	v_lshlrev_b32_e32 v10, 4, v78
	v_lshlrev_b32_e32 v14, 2, v78
	v_and_b32_e32 v10, 0xf0, v10
	v_ashrrev_i32_e32 v15, 31, v14
	v_add_u32_e32 v16, s11, v10
	v_lshl_add_u64 v[10:11], v[14:15], 2, s[0:1]
	global_load_dwordx4 v[116:119], v[10:11], off
	v_add_u32_e32 v15, v16, v17
	v_mov_b32_e32 v128, v15
	v_lshlrev_b32_e32 v10, 2, v20
	v_ashrrev_i32_e32 v11, 31, v10
	v_lshl_add_u64 v[10:11], v[10:11], 2, s[0:1]
	global_load_dwordx4 v[120:123], v[10:11], off
	v_add_u32_e32 v15, v16, v21
	s_and_b32 s1, s2, 0xfffff800
	s_lshl_b32 s0, s7, 4
	s_and_b32 s68, s0, 0x180
	v_mov_b32_e32 v129, v15
	v_or_b32_e32 v11, s1, v80
	v_lshlrev_b32_e32 v12, 3, v78
	v_lshl_add_u32 v76, v82, 8, v11
	v_lshlrev_b32_e32 v10, 4, v82
	v_and_b32_e32 v84, 0x80, v12
	v_and_b32_e32 v12, 0x80, v14
	v_ashrrev_i32_e32 v77, 31, v76
	v_add3_u32 v85, 0, v10, v12
	v_lshlrev_b64 v[10:11], 12, v[76:77]
	v_lshl_add_u64 v[10:11], s[86:87], 0, v[10:11]
	v_lshl_add_u64 v[10:11], v[10:11], 0, s[68:69]
	v_lshl_add_u64 v[10:11], v[10:11], 0, v[74:75]
	v_lshl_add_u64 v[12:13], v[10:11], 0, s[34:35]
	v_add_co_u32_e32 v10, vcc, s95, v10
	v_or_b32_e32 v14, 0x50, v76
	s_nop 0
	v_addc_co_u32_e32 v11, vcc, 0, v11, vcc
	global_load_dwordx4 v[70:73], v[10:11], off offset:1536
	global_load_dwordx4 v[62:65], v[12:13], off offset:64
	v_or_b32_e32 v10, 16, v76
	v_ashrrev_i32_e32 v11, 31, v10
	v_lshlrev_b64 v[10:11], 12, v[10:11]
	v_lshl_add_u64 v[10:11], s[86:87], 0, v[10:11]
	v_lshl_add_u64 v[10:11], v[10:11], 0, s[68:69]
	v_lshl_add_u64 v[10:11], v[10:11], 0, v[74:75]
	v_lshl_add_u64 v[12:13], v[10:11], 0, s[34:35]
	v_add_co_u32_e32 v10, vcc, s95, v10
	v_ashrrev_i32_e32 v15, 31, v14
	s_nop 0
	v_addc_co_u32_e32 v11, vcc, 0, v11, vcc
	global_load_dwordx4 v[66:69], v[10:11], off offset:1536
	global_load_dwordx4 v[54:57], v[12:13], off offset:64
	v_or_b32_e32 v10, 32, v76
	v_ashrrev_i32_e32 v11, 31, v10
	v_lshlrev_b64 v[10:11], 12, v[10:11]
	v_lshl_add_u64 v[10:11], s[86:87], 0, v[10:11]
	v_lshl_add_u64 v[10:11], v[10:11], 0, s[68:69]
	v_lshl_add_u64 v[10:11], v[10:11], 0, v[74:75]
	v_lshl_add_u64 v[12:13], v[10:11], 0, s[34:35]
	v_add_co_u32_e32 v10, vcc, s95, v10
	v_lshlrev_b64 v[14:15], 12, v[14:15]
	s_nop 0
	v_addc_co_u32_e32 v11, vcc, 0, v11, vcc
	global_load_dwordx4 v[58:61], v[10:11], off offset:1536
	global_load_dwordx4 v[38:41], v[12:13], off offset:64
	v_or_b32_e32 v10, 48, v76
	v_ashrrev_i32_e32 v11, 31, v10
	v_lshlrev_b64 v[10:11], 12, v[10:11]
	v_lshl_add_u64 v[10:11], s[86:87], 0, v[10:11]
	v_lshl_add_u64 v[10:11], v[10:11], 0, s[68:69]
	v_lshl_add_u64 v[10:11], v[10:11], 0, v[74:75]
	v_lshl_add_u64 v[12:13], v[10:11], 0, s[34:35]
	v_add_co_u32_e32 v10, vcc, s95, v10
	v_lshl_add_u64 v[14:15], s[86:87], 0, v[14:15]
	s_nop 0
	v_addc_co_u32_e32 v11, vcc, 0, v11, vcc
	global_load_dwordx4 v[50:53], v[10:11], off offset:1536
	global_load_dwordx4 v[22:25], v[12:13], off offset:64
	v_or_b32_e32 v10, 64, v76
	v_ashrrev_i32_e32 v11, 31, v10
	v_lshlrev_b64 v[10:11], 12, v[10:11]
	v_lshl_add_u64 v[10:11], s[86:87], 0, v[10:11]
	v_lshl_add_u64 v[10:11], v[10:11], 0, s[68:69]
	v_lshl_add_u64 v[10:11], v[10:11], 0, v[74:75]
	v_lshl_add_u64 v[12:13], v[10:11], 0, s[34:35]
	v_add_co_u32_e32 v10, vcc, s95, v10
	v_lshl_add_u64 v[14:15], v[14:15], 0, s[68:69]
	v_or_b32_e32 v30, 0x60, v76
	v_addc_co_u32_e32 v11, vcc, 0, v11, vcc
	v_lshl_add_u64 v[14:15], v[14:15], 0, v[74:75]
	v_ashrrev_i32_e32 v31, 31, v30
	v_lshl_add_u64 v[18:19], v[14:15], 0, s[34:35]
	v_add_co_u32_e32 v14, vcc, s95, v14
	v_lshlrev_b64 v[30:31], 12, v[30:31]
	s_nop 0
	v_addc_co_u32_e32 v15, vcc, 0, v15, vcc
	v_lshl_add_u64 v[30:31], s[86:87], 0, v[30:31]
	global_load_dwordx4 v[26:29], v[10:11], off offset:1536
	s_nop 0
	global_load_dwordx4 v[10:13], v[12:13], off offset:64
	s_nop 0
	global_load_dwordx4 v[14:17], v[14:15], off offset:1536
	s_nop 0
	global_load_dwordx4 v[18:21], v[18:19], off offset:64
	v_lshl_add_u64 v[30:31], v[30:31], 0, s[68:69]
	v_lshl_add_u64 v[30:31], v[30:31], 0, v[74:75]
	v_lshl_add_u64 v[34:35], v[30:31], 0, s[34:35]
	v_add_co_u32_e32 v30, vcc, s95, v30
	v_or_b32_e32 v42, 0x70, v76
	s_nop 0
	v_addc_co_u32_e32 v31, vcc, 0, v31, vcc
	global_load_dwordx4 v[30:33], v[30:31], off offset:1536
	s_nop 0
	global_load_dwordx4 v[34:37], v[34:35], off offset:64
	v_ashrrev_i32_e32 v43, 31, v42
	v_lshlrev_b64 v[42:43], 12, v[42:43]
	v_lshl_add_u64 v[42:43], s[86:87], 0, v[42:43]
	v_lshl_add_u64 v[42:43], v[42:43], 0, s[68:69]
	v_lshl_add_u64 v[42:43], v[42:43], 0, v[74:75]
	v_lshl_add_u64 v[46:47], v[42:43], 0, s[34:35]
	v_add_co_u32_e32 v42, vcc, s95, v42
	v_addc_co_u32_e32 v43, vcc, 0, v43, vcc
	global_load_dwordx4 v[42:45], v[42:43], off offset:1536
	s_nop 0
	global_load_dwordx4 v[46:49], v[46:47], off offset:64
	v_or_b32_e32 v204, 0x80, v76
	v_ashrrev_i32_e32 v205, 31, v204
	v_lshlrev_b64 v[204:205], 12, v[204:205]
	v_lshl_add_u64 v[204:205], s[86:87], 0, v[204:205]
	v_lshl_add_u64 v[204:205], v[204:205], 0, s[68:69]
	v_lshl_add_u64 v[204:205], v[204:205], 0, v[74:75]
	v_lshl_add_u64 v[206:207], v[204:205], 0, s[34:35]
	v_add_co_u32_e32 v204, vcc, s95, v204
	v_or_b32_e32 v208, 0xf0, v76
	s_nop 0
	v_addc_co_u32_e32 v205, vcc, 0, v205, vcc
	global_load_dwordx4 v[140:143], v[204:205], off offset:1536
	global_load_dwordx4 v[144:147], v[206:207], off offset:64
	v_or_b32_e32 v204, 0x90, v76
	v_ashrrev_i32_e32 v205, 31, v204
	v_lshlrev_b64 v[204:205], 12, v[204:205]
	v_lshl_add_u64 v[204:205], s[86:87], 0, v[204:205]
	v_lshl_add_u64 v[204:205], v[204:205], 0, s[68:69]
	v_lshl_add_u64 v[204:205], v[204:205], 0, v[74:75]
	v_lshl_add_u64 v[206:207], v[204:205], 0, s[34:35]
	v_add_co_u32_e32 v204, vcc, s95, v204
	v_ashrrev_i32_e32 v209, 31, v208
	s_nop 0
	v_addc_co_u32_e32 v205, vcc, 0, v205, vcc
	global_load_dwordx4 v[148:151], v[204:205], off offset:1536
	global_load_dwordx4 v[152:155], v[206:207], off offset:64
	v_or_b32_e32 v204, 0xa0, v76
	v_ashrrev_i32_e32 v205, 31, v204
	v_lshlrev_b64 v[204:205], 12, v[204:205]
	v_lshl_add_u64 v[204:205], s[86:87], 0, v[204:205]
	v_lshl_add_u64 v[204:205], v[204:205], 0, s[68:69]
	v_lshl_add_u64 v[204:205], v[204:205], 0, v[74:75]
	v_lshl_add_u64 v[206:207], v[204:205], 0, s[34:35]
	v_add_co_u32_e32 v204, vcc, s95, v204
	v_lshlrev_b64 v[208:209], 12, v[208:209]
	s_nop 0
	v_addc_co_u32_e32 v205, vcc, 0, v205, vcc
	global_load_dwordx4 v[156:159], v[204:205], off offset:1536
	global_load_dwordx4 v[160:163], v[206:207], off offset:64
	v_or_b32_e32 v204, 0xb0, v76
	v_ashrrev_i32_e32 v205, 31, v204
	v_lshlrev_b64 v[204:205], 12, v[204:205]
	v_lshl_add_u64 v[204:205], s[86:87], 0, v[204:205]
	v_lshl_add_u64 v[204:205], v[204:205], 0, s[68:69]
	v_lshl_add_u64 v[204:205], v[204:205], 0, v[74:75]
	v_lshl_add_u64 v[206:207], v[204:205], 0, s[34:35]
	v_add_co_u32_e32 v204, vcc, s95, v204
	v_lshl_add_u64 v[208:209], s[86:87], 0, v[208:209]
	s_nop 0
	v_addc_co_u32_e32 v205, vcc, 0, v205, vcc
	global_load_dwordx4 v[164:167], v[204:205], off offset:1536
	global_load_dwordx4 v[168:171], v[206:207], off offset:64
	v_or_b32_e32 v204, 0xc0, v76
	v_ashrrev_i32_e32 v205, 31, v204
	v_lshlrev_b64 v[204:205], 12, v[204:205]
	v_lshl_add_u64 v[204:205], s[86:87], 0, v[204:205]
	v_lshl_add_u64 v[204:205], v[204:205], 0, s[68:69]
	v_lshl_add_u64 v[204:205], v[204:205], 0, v[74:75]
	v_lshl_add_u64 v[206:207], v[204:205], 0, s[34:35]
	v_add_co_u32_e32 v204, vcc, s95, v204
	v_lshl_add_u64 v[208:209], v[208:209], 0, s[68:69]
	s_nop 0
	v_addc_co_u32_e32 v205, vcc, 0, v205, vcc
	global_load_dwordx4 v[172:175], v[204:205], off offset:1536
	global_load_dwordx4 v[176:179], v[206:207], off offset:64
	v_or_b32_e32 v204, 0xd0, v76
	v_ashrrev_i32_e32 v205, 31, v204
	v_lshlrev_b64 v[204:205], 12, v[204:205]
	v_lshl_add_u64 v[204:205], s[86:87], 0, v[204:205]
	v_lshl_add_u64 v[204:205], v[204:205], 0, s[68:69]
	v_lshl_add_u64 v[204:205], v[204:205], 0, v[74:75]
	v_lshl_add_u64 v[206:207], v[204:205], 0, s[34:35]
	v_add_co_u32_e32 v204, vcc, s95, v204
	v_lshl_add_u64 v[208:209], v[208:209], 0, v[74:75]
	s_nop 0
	v_addc_co_u32_e32 v205, vcc, 0, v205, vcc
	global_load_dwordx4 v[180:183], v[204:205], off offset:1536
	global_load_dwordx4 v[184:187], v[206:207], off offset:64
	v_or_b32_e32 v204, 0xe0, v76
	v_ashrrev_i32_e32 v205, 31, v204
	v_lshlrev_b64 v[204:205], 12, v[204:205]
	v_lshl_add_u64 v[204:205], s[86:87], 0, v[204:205]
	v_lshl_add_u64 v[204:205], v[204:205], 0, s[68:69]
	v_lshl_add_u64 v[204:205], v[204:205], 0, v[74:75]
	v_lshl_add_u64 v[206:207], v[204:205], 0, s[34:35]
	v_add_co_u32_e32 v204, vcc, s95, v204
	v_lshl_add_u64 v[210:211], v[208:209], 0, s[34:35]
	s_nop 0
	v_addc_co_u32_e32 v205, vcc, 0, v205, vcc
	global_load_dwordx4 v[188:191], v[204:205], off offset:1536
	s_nop 0
	global_load_dwordx4 v[192:195], v[206:207], off offset:64
	v_add_co_u32_e32 v208, vcc, s95, v208
	v_addc_co_u32_e32 v209, vcc, 0, v209, vcc
	global_load_dwordx4 v[196:199], v[208:209], off offset:1536
	s_nop 0
	global_load_dwordx4 v[216:219], v[210:211], off offset:64
	s_waitcnt vmcnt(32)
	ds_write_b128 v124, v[100:103]
	ds_write_b128 v125, v[104:107]
	ds_write_b128 v126, v[108:111]
	ds_write_b128 v127, v[112:115]
	ds_write_b128 v128, v[116:119]
	ds_write_b128 v129, v[120:123]
	s_waitcnt vmcnt(21)
	v_mfma_f32_16x16x32_bf16 v[14:17], v[6:9], v[14:17], 0
	v_mfma_f32_16x16x32_bf16 v[26:29], v[6:9], v[26:29], 0
	s_waitcnt vmcnt(20)
	v_mfma_f32_16x16x32_bf16 v[14:17], v[2:5], v[18:21], v[14:17]
	s_waitcnt vmcnt(19)
	v_mfma_f32_16x16x32_bf16 v[18:21], v[6:9], v[30:33], 0
	v_mfma_f32_16x16x32_bf16 v[70:73], v[6:9], v[70:73], 0
	v_mfma_f32_16x16x32_bf16 v[58:61], v[6:9], v[58:61], 0
	v_mfma_f32_16x16x32_bf16 v[10:13], v[2:5], v[10:13], v[26:29]
	s_waitcnt vmcnt(18)
	v_mfma_f32_16x16x32_bf16 v[18:21], v[2:5], v[34:37], v[18:21]
	v_mfma_f32_16x16x32_bf16 v[62:65], v[2:5], v[62:65], v[70:73]
	v_mfma_f32_16x16x32_bf16 v[38:41], v[2:5], v[38:41], v[58:61]
	s_nop 5
	v_cvt_pk_bf16_f32 v31, v10, v18
	v_or_b32_e32 v18, 32, v84
	v_or_b32_e32 v10, v84, v80
	s_waitcnt vmcnt(17)
	v_mfma_f32_16x16x32_bf16 v[26:29], v[6:9], v[42:45], 0
	v_cvt_pk_bf16_f32 v11, v11, v19
	v_or_b32_e32 v19, v18, v80
	v_cvt_pk_bf16_f32 v30, v62, v38
	v_mfma_f32_16x16x32_bf16 v[66:69], v[6:9], v[66:69], 0
	v_mad_u32_u24 v38, v10, s31, v85
	v_cvt_pk_bf16_f32 v10, v63, v39
	v_mad_u32_u24 v39, v19, s31, v85
	v_mfma_f32_16x16x32_bf16 v[50:53], v[6:9], v[50:53], 0
	ds_write_b64 v38, v[30:31]
	ds_write_b64 v39, v[10:11]
	v_cvt_pk_bf16_f32 v11, v12, v20
	v_or_b32_e32 v12, 64, v84
	v_or_b32_e32 v19, v12, v80
	s_waitcnt vmcnt(16)
	v_mfma_f32_16x16x32_bf16 v[26:29], v[2:5], v[46:49], v[26:29]
	v_cvt_pk_bf16_f32 v10, v64, v40
	v_mad_u32_u24 v40, v19, s31, v85
	ds_write_b64 v40, v[10:11]
	v_mfma_f32_16x16x32_bf16 v[54:57], v[2:5], v[54:57], v[66:69]
	v_cvt_pk_bf16_f32 v11, v13, v21
	v_or_b32_e32 v13, 0x60, v84
	v_or_b32_e32 v19, v13, v80
	v_mfma_f32_16x16x32_bf16 v[22:25], v[2:5], v[22:25], v[50:53]
	v_cvt_pk_bf16_f32 v10, v65, v41
	v_mad_u32_u24 v41, v19, s31, v85
	v_or_b32_e32 v72, 16, v80
	ds_write_b64 v41, v[10:11]
	v_cvt_pk_bf16_f32 v11, v14, v26
	v_or_b32_e32 v14, v84, v72
	s_nop 1
	v_cvt_pk_bf16_f32 v10, v54, v22
	v_mad_u32_u24 v42, v14, s31, v85
	v_or_b32_e32 v14, v18, v72
	ds_write_b64 v42, v[10:11]
	v_cvt_pk_bf16_f32 v10, v55, v23
	v_cvt_pk_bf16_f32 v11, v15, v27
	v_mad_u32_u24 v43, v14, s31, v85
	v_or_b32_e32 v12, v12, v72
	ds_write_b64 v43, v[10:11]
	v_cvt_pk_bf16_f32 v10, v56, v24
	v_cvt_pk_bf16_f32 v11, v16, v28
	v_mad_u32_u24 v44, v12, s31, v85
	v_or_b32_e32 v12, v13, v72
	ds_write_b64 v44, v[10:11]
	v_cvt_pk_bf16_f32 v10, v57, v25
	v_cvt_pk_bf16_f32 v11, v17, v29
	v_mad_u32_u24 v45, v12, s31, v85
	ds_write_b64 v45, v[10:11]
	s_waitcnt vmcnt(15)
	v_mfma_f32_16x16x32_bf16 v[46:49], v[6:9], v[140:143], 0
	s_waitcnt vmcnt(14)
	v_mfma_f32_16x16x32_bf16 v[46:49], v[2:5], v[144:147], v[46:49]
	s_waitcnt vmcnt(13)
	v_mfma_f32_16x16x32_bf16 v[50:53], v[6:9], v[148:151], 0
	s_waitcnt vmcnt(11)
	v_mfma_f32_16x16x32_bf16 v[54:57], v[6:9], v[156:159], 0
	s_waitcnt vmcnt(7)
	v_mfma_f32_16x16x32_bf16 v[62:65], v[6:9], v[172:175], 0
	s_waitcnt vmcnt(3)
	v_mfma_f32_16x16x32_bf16 v[26:29], v[6:9], v[188:191], 0
	v_mfma_f32_16x16x32_bf16 v[50:53], v[2:5], v[152:155], v[50:53]
	v_mfma_f32_16x16x32_bf16 v[54:57], v[2:5], v[160:163], v[54:57]
	v_mfma_f32_16x16x32_bf16 v[58:61], v[6:9], v[164:167], 0
	v_mfma_f32_16x16x32_bf16 v[30:33], v[2:5], v[176:179], v[62:65]
	v_mfma_f32_16x16x32_bf16 v[34:37], v[6:9], v[180:183], 0
	s_waitcnt vmcnt(2)
	v_mfma_f32_16x16x32_bf16 v[10:13], v[2:5], v[192:195], v[26:29]
	s_waitcnt vmcnt(1)
	v_mfma_f32_16x16x32_bf16 v[6:9], v[6:9], v[196:199], 0
	v_mfma_f32_16x16x32_bf16 v[58:61], v[2:5], v[168:171], v[58:61]
	v_mfma_f32_16x16x32_bf16 v[22:25], v[2:5], v[184:187], v[34:37]
	s_waitcnt vmcnt(0)
	v_mfma_f32_16x16x32_bf16 v[2:5], v[2:5], v[216:219], v[6:9]
	v_lshl_or_b32 v18, v82, 5, v80
	v_mul_lo_u32 v18, v18, s31
	v_mov_b32_e32 v36, 0x1100
	s_nop 0
	v_cvt_pk_bf16_f32 v6, v46, v54
	v_cvt_pk_bf16_f32 v7, v30, v10
	ds_write_b64 v38, v[6:7] offset:8
	v_cvt_pk_bf16_f32 v6, v47, v55
	v_cvt_pk_bf16_f32 v7, v31, v11
	ds_write_b64 v39, v[6:7] offset:8
	v_cvt_pk_bf16_f32 v6, v48, v56
	v_cvt_pk_bf16_f32 v7, v32, v12
	ds_write_b64 v40, v[6:7] offset:8
	v_cvt_pk_bf16_f32 v6, v49, v57
	v_cvt_pk_bf16_f32 v7, v33, v13
	ds_write_b64 v41, v[6:7] offset:8
	v_cvt_pk_bf16_f32 v6, v50, v58
	v_cvt_pk_bf16_f32 v7, v22, v2
	v_cvt_pk_bf16_f32 v2, v51, v59
	v_cvt_pk_bf16_f32 v3, v23, v3
	ds_write_b64 v42, v[6:7] offset:8
	ds_write_b64 v43, v[2:3] offset:8
	v_cvt_pk_bf16_f32 v2, v52, v60
	v_cvt_pk_bf16_f32 v3, v24, v4
	ds_write_b64 v44, v[2:3] offset:8
	v_cvt_pk_bf16_f32 v2, v53, v61
	v_cvt_pk_bf16_f32 v3, v25, v5
	v_mov_b32_e32 v44, 0x2200
	v_mov_b32_e32 v53, 0x3300
	ds_write_b64 v45, v[2:3] offset:8
	v_lshl_add_u64 v[2:3], s[8:9], 0, v[74:75]
	v_add3_u32 v31, 0, v18, v74
	v_add_u32_e32 v52, s10, v74
	v_mad_u32_u24 v75, v80, s31, v36
	v_mad_u32_u24 v74, v80, s31, v44
	v_mad_u32_u24 v73, v80, s31, v53
	v_lshl_add_u64 v[2:3], v[2:3], 0, v[98:99]
	v_mad_u32_u24 v30, v80, s31, v52
	v_add_u32_e32 v76, v52, v75
	v_add_u32_e32 v77, v52, v74
	v_add_u32_e32 v96, v52, v73
	global_load_dwordx4 v[10:13], v[2:3], off
	global_load_dwordx4 v[6:9], v[2:3], off offset:64
	global_load_dwordx4 v[14:17], v[2:3], off offset:2048
	s_nop 0
	global_load_dwordx4 v[2:5], v[2:3], off offset:2112
	s_waitcnt lgkmcnt(0)
	s_barrier
	ds_read_b128 v[18:21], v31
	ds_read_b128 v[22:25], v31 offset:4352
	ds_read_b128 v[26:29], v30
	ds_read_b128 v[60:63], v30 offset:17408
	ds_read_b128 v[36:39], v76
	ds_read_b128 v[100:103], v30 offset:30464
	ds_read_b128 v[44:47], v77
	ds_read_b128 v[52:55], v96
	ds_read_b128 v[68:71], v30 offset:21760
	ds_read_b128 v[88:91], v30 offset:26112
	s_waitcnt lgkmcnt(7)
	v_mfma_f32_16x16x32_bf16 v[32:35], v[18:21], v[26:29], 0
	s_movk_i32 s10, 0x90
	v_bfe_u32 v98, v78, 1, 3
	v_mfma_f32_16x16x32_bf16 v[26:29], v[22:25], v[26:29], 0
	s_waitcnt lgkmcnt(5)
	v_mfma_f32_16x16x32_bf16 v[40:43], v[18:21], v[36:39], 0
	v_mfma_f32_16x16x32_bf16 v[36:39], v[22:25], v[36:39], 0
	s_waitcnt lgkmcnt(3)
	v_mfma_f32_16x16x32_bf16 v[48:51], v[18:21], v[44:47], 0
	v_mfma_f32_16x16x32_bf16 v[44:47], v[22:25], v[44:47], 0
	s_waitcnt lgkmcnt(2)
	v_mfma_f32_16x16x32_bf16 v[56:59], v[18:21], v[52:55], 0
	v_mfma_f32_16x16x32_bf16 v[52:55], v[22:25], v[52:55], 0
	v_mfma_f32_16x16x32_bf16 v[64:67], v[18:21], v[60:63], 0
	v_mfma_f32_16x16x32_bf16 v[60:63], v[22:25], v[60:63], 0
	s_waitcnt lgkmcnt(1)
	v_mfma_f32_16x16x32_bf16 v[84:87], v[18:21], v[68:71], 0
	v_mfma_f32_16x16x32_bf16 v[68:71], v[22:25], v[68:71], 0
	s_waitcnt lgkmcnt(0)
	v_mfma_f32_16x16x32_bf16 v[92:95], v[18:21], v[88:91], 0
	v_mfma_f32_16x16x32_bf16 v[88:91], v[22:25], v[88:91], 0
	v_mfma_f32_16x16x32_bf16 v[18:21], v[18:21], v[100:103], 0
	v_mfma_f32_16x16x32_bf16 v[22:25], v[22:25], v[100:103], 0
	ds_read_b128 v[100:103], v31 offset:64
	ds_read_b128 v[104:107], v31 offset:4416
	ds_read_b128 v[108:111], v30 offset:64
	s_waitcnt lgkmcnt(0)
	v_mfma_f32_16x16x32_bf16 v[32:35], v[100:103], v[108:111], v[32:35]
	v_mfma_f32_16x16x32_bf16 v[26:29], v[104:107], v[108:111], v[26:29]
	ds_read_b128 v[108:111], v76 offset:64
	s_waitcnt lgkmcnt(0)
	v_mfma_f32_16x16x32_bf16 v[40:43], v[100:103], v[108:111], v[40:43]
	v_mfma_f32_16x16x32_bf16 v[36:39], v[104:107], v[108:111], v[36:39]
	ds_read_b128 v[108:111], v77 offset:64
	s_waitcnt lgkmcnt(0)
	v_mfma_f32_16x16x32_bf16 v[48:51], v[100:103], v[108:111], v[48:51]
	v_mfma_f32_16x16x32_bf16 v[44:47], v[104:107], v[108:111], v[44:47]
	ds_read_b128 v[108:111], v96 offset:64
	s_waitcnt lgkmcnt(0)
	v_mfma_f32_16x16x32_bf16 v[56:59], v[100:103], v[108:111], v[56:59]
	v_mfma_f32_16x16x32_bf16 v[52:55], v[104:107], v[108:111], v[52:55]
	ds_read_b128 v[108:111], v30 offset:17472
	s_waitcnt lgkmcnt(0)
	v_mfma_f32_16x16x32_bf16 v[64:67], v[100:103], v[108:111], v[64:67]
	v_mfma_f32_16x16x32_bf16 v[60:63], v[104:107], v[108:111], v[60:63]
	ds_read_b128 v[108:111], v30 offset:21824
	s_waitcnt lgkmcnt(0)
	v_mfma_f32_16x16x32_bf16 v[84:87], v[100:103], v[108:111], v[84:87]
	v_mfma_f32_16x16x32_bf16 v[68:71], v[104:107], v[108:111], v[68:71]
	ds_read_b128 v[108:111], v30 offset:26176
	s_waitcnt lgkmcnt(0)
	v_mfma_f32_16x16x32_bf16 v[92:95], v[100:103], v[108:111], v[92:95]
	v_mfma_f32_16x16x32_bf16 v[88:91], v[104:107], v[108:111], v[88:91]
	ds_read_b128 v[108:111], v30 offset:30528
	s_waitcnt lgkmcnt(0)
	v_mfma_f32_16x16x32_bf16 v[18:21], v[100:103], v[108:111], v[18:21]
	v_mfma_f32_16x16x32_bf16 v[22:25], v[104:107], v[108:111], v[22:25]
	ds_read_b128 v[100:103], v31 offset:128
	ds_read_b128 v[104:107], v31 offset:4480
	ds_read_b128 v[108:111], v30 offset:128
	s_waitcnt lgkmcnt(0)
	v_mfma_f32_16x16x32_bf16 v[32:35], v[100:103], v[108:111], v[32:35]
	v_mfma_f32_16x16x32_bf16 v[26:29], v[104:107], v[108:111], v[26:29]
	ds_read_b128 v[108:111], v76 offset:128
	s_waitcnt lgkmcnt(0)
	v_mfma_f32_16x16x32_bf16 v[40:43], v[100:103], v[108:111], v[40:43]
	v_mfma_f32_16x16x32_bf16 v[36:39], v[104:107], v[108:111], v[36:39]
	ds_read_b128 v[108:111], v77 offset:128
	s_waitcnt lgkmcnt(0)
	v_mfma_f32_16x16x32_bf16 v[112:115], v[100:103], v[108:111], v[48:51]
	v_mfma_f32_16x16x32_bf16 v[46:49], v[104:107], v[108:111], v[44:47]
	ds_read_b128 v[108:111], v96 offset:128
	s_waitcnt lgkmcnt(0)
	v_mfma_f32_16x16x32_bf16 v[56:59], v[100:103], v[108:111], v[56:59]
	v_mfma_f32_16x16x32_bf16 v[108:111], v[104:107], v[108:111], v[52:55]
	s_nop 2
	ds_read_b128 v[50:53], v30 offset:17536
	s_waitcnt lgkmcnt(0)
	v_mfma_f32_16x16x32_bf16 v[116:119], v[100:103], v[50:53], v[64:67]
	v_mfma_f32_16x16x32_bf16 v[120:123], v[104:107], v[50:53], v[60:63]
	ds_read_b128 v[50:53], v30 offset:21888
	s_waitcnt lgkmcnt(0)
	v_mfma_f32_16x16x32_bf16 v[84:87], v[100:103], v[50:53], v[84:87]
	v_mfma_f32_16x16x32_bf16 v[124:127], v[104:107], v[50:53], v[68:71]
	ds_read_b128 v[50:53], v30 offset:26240
	s_waitcnt lgkmcnt(0)
	v_mfma_f32_16x16x32_bf16 v[92:95], v[100:103], v[50:53], v[92:95]
	v_mfma_f32_16x16x32_bf16 v[88:91], v[104:107], v[50:53], v[88:91]
	ds_read_b128 v[50:53], v30 offset:30592
	s_waitcnt lgkmcnt(0)
	v_mfma_f32_16x16x32_bf16 v[100:103], v[100:103], v[50:53], v[18:21]
	ds_read_b128 v[128:131], v31 offset:192
	ds_read_b128 v[132:135], v31 offset:4544
	s_nop 0
	ds_read_b128 v[18:21], v30 offset:192
	s_waitcnt lgkmcnt(0)
	v_mfma_f32_16x16x32_bf16 v[136:139], v[128:131], v[18:21], v[32:35]
	v_mfma_f32_16x16x32_bf16 v[62:65], v[132:135], v[18:21], v[26:29]
	ds_read_b128 v[18:21], v76 offset:192
	v_bfe_u32 v76, v83, 1, 1
	v_mfma_f32_16x16x32_bf16 v[104:107], v[104:107], v[50:53], v[22:25]
	s_waitcnt lgkmcnt(0)
	v_mfma_f32_16x16x32_bf16 v[50:53], v[128:131], v[18:21], v[40:43]
	v_mfma_f32_16x16x32_bf16 v[42:45], v[132:135], v[18:21], v[36:39]
	ds_read_b128 v[18:21], v77 offset:192
	s_nop 1
	ds_read_b128 v[38:41], v30 offset:17600
	s_waitcnt lgkmcnt(1)
	v_mfma_f32_16x16x32_bf16 v[34:37], v[128:131], v[18:21], v[112:115]
	v_lshl_add_u32 v77, v81, 5, s11
	v_mad_u32_u24 v83, v80, s31, v77
	v_add_u32_e32 v75, v77, v75
	v_mfma_f32_16x16x32_bf16 v[26:29], v[132:135], v[18:21], v[46:49]
	ds_read_b128 v[18:21], v96 offset:192
	s_waitcnt lgkmcnt(0)
	v_mfma_f32_16x16x32_bf16 v[22:25], v[128:131], v[18:21], v[56:59]
	v_mfma_f32_16x16x32_bf16 v[18:21], v[132:135], v[18:21], v[108:111]
	v_mfma_f32_16x16x32_bf16 v[108:111], v[128:131], v[38:41], v[116:119]
	v_mfma_f32_16x16x32_bf16 v[112:115], v[132:135], v[38:41], v[120:123]
	ds_read_b128 v[38:41], v30 offset:21952
	s_waitcnt lgkmcnt(0)
	v_mfma_f32_16x16x32_bf16 v[66:69], v[128:131], v[38:41], v[84:87]
	v_mfma_f32_16x16x32_bf16 v[58:61], v[132:135], v[38:41], v[124:127]
	ds_read_b128 v[38:41], v30 offset:26304
	ds_read_b128 v[30:33], v30 offset:30656
	s_waitcnt lgkmcnt(0)
	v_mfma_f32_16x16x32_bf16 v[46:49], v[132:135], v[38:41], v[88:91]
	s_barrier
	ds_read_b128 v[84:87], v83
	s_nop 0
	ds_read_b128 v[88:91], v83 offset:16
	v_mfma_f32_16x16x32_bf16 v[54:57], v[128:131], v[38:41], v[92:95]
	s_waitcnt lgkmcnt(0)
	v_mov_b32_e32 v97, v90
	s_nop 0
	v_lshrrev_b32_e32 v93, 1, v78
	v_mov_b32_e32 v95, v86
	v_mov_b32_e32 v86, v85
	v_mov_b32_e32 v90, v89
	v_and_b32_e32 v70, 8, v93
	v_mov_b32_e32 v94, v84
	v_pk_mul_f32 v[84:85], v[108:109], v[86:87]
	v_mov_b32_e32 v96, v88
	v_pk_mul_f32 v[88:89], v[110:111], v[90:91]
	v_add_u32_e32 v92, 0, v70
	v_lshl_add_u32 v70, v80, 3, v82
	v_pk_fma_f32 v[84:85], v[136:137], v[94:95], v[84:85] neg_lo:[0,0,1] neg_hi:[0,0,1]
	v_pk_fma_f32 v[88:89], v[138:139], v[96:97], v[88:89] neg_lo:[0,0,1] neg_hi:[0,0,1]
	v_mad_u64_u32 v[70:71], s[8:9], v70, s10, v[92:93]
	v_cvt_pk_bf16_f32 v84, v84, v85
	v_cvt_pk_bf16_f32 v85, v88, v89
	v_pk_mul_f32 v[88:89], v[108:109], v[94:95]
	v_bitop3_b32 v71, v76, v93, 7 bitop3:0x78
	v_pk_fma_f32 v[86:87], v[136:137], v[86:87], v[88:89]
	v_pk_mul_f32 v[88:89], v[110:111], v[96:97]
	v_lshlrev_b32_e32 v71, 4, v71
	v_pk_fma_f32 v[88:89], v[138:139], v[90:91], v[88:89]
	v_cvt_pk_bf16_f32 v86, v86, v87
	v_cvt_pk_bf16_f32 v87, v88, v89
	v_add_u32_e32 v88, v70, v71
	ds_write_b64 v88, v[84:85]
	v_bitop3_b32 v84, v76, v98, 4 bitop3:0x36
	v_mfma_f32_16x16x32_bf16 v[38:41], v[128:131], v[30:33], v[100:103]
	s_nop 2
	v_lshlrev_b32_e32 v100, 4, v84
	v_add_u32_e32 v84, v70, v100
	ds_write_b64 v84, v[86:87]
	ds_read_b128 v[84:87], v83 offset:128
	ds_read_b128 v[88:91], v83 offset:144
	v_mfma_f32_16x16x32_bf16 v[30:33], v[132:135], v[30:33], v[104:107]
	s_waitcnt lgkmcnt(1)
	v_mov_b32_e32 v95, v86
	v_mov_b32_e32 v86, v85
	s_waitcnt lgkmcnt(0)
	v_mov_b32_e32 v97, v90
	v_mov_b32_e32 v90, v89
	v_mov_b32_e32 v94, v84
	v_pk_mul_f32 v[84:85], v[112:113], v[86:87]
	v_mov_b32_e32 v96, v88
	v_pk_mul_f32 v[88:89], v[114:115], v[90:91]
	v_pk_fma_f32 v[84:85], v[62:63], v[94:95], v[84:85] neg_lo:[0,0,1] neg_hi:[0,0,1]
	v_pk_fma_f32 v[88:89], v[64:65], v[96:97], v[88:89] neg_lo:[0,0,1] neg_hi:[0,0,1]
	v_cvt_pk_bf16_f32 v84, v84, v85
	v_cvt_pk_bf16_f32 v85, v88, v89
	v_pk_mul_f32 v[88:89], v[112:113], v[94:95]
	s_nop 0
	v_pk_fma_f32 v[62:63], v[62:63], v[86:87], v[88:89]
	v_pk_mul_f32 v[86:87], v[114:115], v[96:97]
	v_cvt_pk_bf16_f32 v62, v62, v63
	v_pk_fma_f32 v[64:65], v[64:65], v[90:91], v[86:87]
	s_nop 0
	v_cvt_pk_bf16_f32 v63, v64, v65
	v_bitop3_b32 v64, v76, v98, 2 bitop3:0x36
	v_lshlrev_b32_e32 v83, 4, v64
	v_add_u32_e32 v64, v70, v83
	ds_write_b64 v64, v[84:85]
	v_bitop3_b32 v64, v76, v98, 6 bitop3:0x36
	v_lshlrev_b32_e32 v94, 4, v64
	v_add_u32_e32 v64, v70, v94
	ds_write_b64 v64, v[62:63]
	v_lshl_add_u32 v62, v72, 3, v82
	v_mad_u64_u32 v[88:89], s[8:9], v62, s10, v[92:93]
	ds_read_b128 v[62:65], v75
	ds_read_b128 v[84:87], v75 offset:16
	s_waitcnt lgkmcnt(1)
	v_mov_b32_e32 v90, v62
	v_mov_b32_e32 v91, v64
	v_mov_b32_e32 v64, v63
	v_pk_mul_f32 v[62:63], v[66:67], v[64:65]
	s_waitcnt lgkmcnt(0)
	v_mov_b32_e32 v92, v84
	v_mov_b32_e32 v93, v86
	v_mov_b32_e32 v86, v85
	v_pk_mul_f32 v[66:67], v[66:67], v[90:91]
	v_pk_fma_f32 v[62:63], v[50:51], v[90:91], v[62:63] neg_lo:[0,0,1] neg_hi:[0,0,1]
	v_pk_mul_f32 v[84:85], v[68:69], v[86:87]
	v_pk_fma_f32 v[50:51], v[50:51], v[64:65], v[66:67]
	v_pk_mul_f32 v[64:65], v[68:69], v[92:93]
	v_pk_fma_f32 v[84:85], v[52:53], v[92:93], v[84:85] neg_lo:[0,0,1] neg_hi:[0,0,1]
	v_pk_fma_f32 v[52:53], v[52:53], v[86:87], v[64:65]
	v_cvt_pk_bf16_f32 v62, v62, v63
	v_cvt_pk_bf16_f32 v63, v84, v85
	v_cvt_pk_bf16_f32 v50, v50, v51
	v_cvt_pk_bf16_f32 v51, v52, v53
	v_add_u32_e32 v52, v88, v71
	ds_write_b64 v52, v[62:63]
	v_add_u32_e32 v52, v88, v100
	ds_write_b64 v52, v[50:51]
	ds_read_b128 v[50:53], v75 offset:128
	ds_read_b128 v[62:65], v75 offset:144
	s_waitcnt lgkmcnt(1)
	v_mov_b32_e32 v66, v50
	v_mov_b32_e32 v67, v52
	v_mov_b32_e32 v52, v51
	v_pk_mul_f32 v[50:51], v[58:59], v[52:53]
	s_waitcnt lgkmcnt(0)
	v_mov_b32_e32 v68, v62
	v_mov_b32_e32 v69, v64
	v_mov_b32_e32 v64, v63
	v_pk_mul_f32 v[58:59], v[58:59], v[66:67]
	v_pk_fma_f32 v[50:51], v[42:43], v[66:67], v[50:51] neg_lo:[0,0,1] neg_hi:[0,0,1]
	v_pk_mul_f32 v[62:63], v[60:61], v[64:65]
	v_pk_fma_f32 v[42:43], v[42:43], v[52:53], v[58:59]
	v_pk_mul_f32 v[52:53], v[60:61], v[68:69]
	v_pk_fma_f32 v[62:63], v[44:45], v[68:69], v[62:63] neg_lo:[0,0,1] neg_hi:[0,0,1]
	v_pk_fma_f32 v[44:45], v[44:45], v[64:65], v[52:53]
	v_cvt_pk_bf16_f32 v50, v50, v51
	v_cvt_pk_bf16_f32 v51, v62, v63
	v_cvt_pk_bf16_f32 v42, v42, v43
	v_cvt_pk_bf16_f32 v43, v44, v45
	v_add_u32_e32 v44, v88, v83
	ds_write_b64 v44, v[50:51]
	v_add_u32_e32 v44, v88, v94
	ds_write_b64 v44, v[42:43]
	v_add_u32_e32 v62, v77, v74
	ds_read_b128 v[42:45], v62
	ds_read_b128 v[50:53], v62 offset:16
	v_add_u32_e32 v63, 0x9000, v70
	s_waitcnt lgkmcnt(1)
	v_mov_b32_e32 v59, v44
	v_mov_b32_e32 v44, v43
	s_waitcnt lgkmcnt(0)
	v_mov_b32_e32 v61, v52
	v_mov_b32_e32 v52, v51
	v_mov_b32_e32 v58, v42
	v_pk_mul_f32 v[42:43], v[54:55], v[44:45]
	v_mov_b32_e32 v60, v50
	v_pk_mul_f32 v[50:51], v[56:57], v[52:53]
	v_pk_fma_f32 v[42:43], v[34:35], v[58:59], v[42:43] neg_lo:[0,0,1] neg_hi:[0,0,1]
	v_pk_fma_f32 v[50:51], v[36:37], v[60:61], v[50:51] neg_lo:[0,0,1] neg_hi:[0,0,1]
	v_cvt_pk_bf16_f32 v42, v42, v43
	v_cvt_pk_bf16_f32 v43, v50, v51
	v_pk_mul_f32 v[50:51], v[54:55], v[58:59]
	s_nop 0
	v_pk_fma_f32 v[34:35], v[34:35], v[44:45], v[50:51]
	v_pk_mul_f32 v[44:45], v[56:57], v[60:61]
	v_cvt_pk_bf16_f32 v34, v34, v35
	v_pk_fma_f32 v[36:37], v[36:37], v[52:53], v[44:45]
	s_nop 0
	v_cvt_pk_bf16_f32 v35, v36, v37
	v_add_u32_e32 v36, v63, v71
	ds_write_b64 v36, v[42:43]
	v_add_u32_e32 v36, v63, v100
	ds_write_b64 v36, v[34:35]
	ds_read_b128 v[34:37], v62 offset:128
	ds_read_b128 v[42:45], v62 offset:144
	s_waitcnt lgkmcnt(1)
	v_mov_b32_e32 v51, v36
	v_mov_b32_e32 v36, v35
	s_waitcnt lgkmcnt(0)
	v_mov_b32_e32 v53, v44
	v_mov_b32_e32 v44, v43
	v_mov_b32_e32 v50, v34
	v_pk_mul_f32 v[34:35], v[46:47], v[36:37]
	v_mov_b32_e32 v52, v42
	v_pk_mul_f32 v[42:43], v[48:49], v[44:45]
	v_pk_fma_f32 v[34:35], v[26:27], v[50:51], v[34:35] neg_lo:[0,0,1] neg_hi:[0,0,1]
	v_pk_fma_f32 v[42:43], v[28:29], v[52:53], v[42:43] neg_lo:[0,0,1] neg_hi:[0,0,1]
	v_cvt_pk_bf16_f32 v34, v34, v35
	v_cvt_pk_bf16_f32 v35, v42, v43
	v_pk_mul_f32 v[42:43], v[46:47], v[50:51]
	v_add_u32_e32 v46, v77, v73
	v_pk_fma_f32 v[26:27], v[26:27], v[36:37], v[42:43]
	v_pk_mul_f32 v[36:37], v[48:49], v[52:53]
	v_cvt_pk_bf16_f32 v26, v26, v27
	v_pk_fma_f32 v[28:29], v[28:29], v[44:45], v[36:37]
	v_add_u32_e32 v47, 0xd800, v70
	v_cvt_pk_bf16_f32 v27, v28, v29
	v_add_u32_e32 v28, v63, v83
	ds_write_b64 v28, v[34:35]
	v_add_u32_e32 v28, v63, v94
	ds_write_b64 v28, v[26:27]
	ds_read_b128 v[26:29], v46
	ds_read_b128 v[34:37], v46 offset:16
	s_waitcnt lgkmcnt(1)
	v_mov_b32_e32 v43, v28
	v_mov_b32_e32 v28, v27
	s_waitcnt lgkmcnt(0)
	v_mov_b32_e32 v45, v36
	v_mov_b32_e32 v36, v35
	v_mov_b32_e32 v42, v26
	v_pk_mul_f32 v[26:27], v[38:39], v[28:29]
	v_mov_b32_e32 v44, v34
	v_pk_mul_f32 v[34:35], v[40:41], v[36:37]
	v_pk_fma_f32 v[26:27], v[22:23], v[42:43], v[26:27] neg_lo:[0,0,1] neg_hi:[0,0,1]
	v_pk_fma_f32 v[34:35], v[24:25], v[44:45], v[34:35] neg_lo:[0,0,1] neg_hi:[0,0,1]
	v_cvt_pk_bf16_f32 v26, v26, v27
	v_cvt_pk_bf16_f32 v27, v34, v35
	v_pk_mul_f32 v[34:35], v[38:39], v[42:43]
	s_nop 0
	v_pk_fma_f32 v[22:23], v[22:23], v[28:29], v[34:35]
	v_pk_mul_f32 v[28:29], v[40:41], v[44:45]
	v_cvt_pk_bf16_f32 v22, v22, v23
	v_pk_fma_f32 v[24:25], v[24:25], v[36:37], v[28:29]
	s_nop 0
	v_cvt_pk_bf16_f32 v23, v24, v25
	v_add_u32_e32 v24, v47, v71
	ds_write_b64 v24, v[26:27]
	v_add_u32_e32 v24, v47, v100
	ds_write_b64 v24, v[22:23]
	ds_read_b128 v[22:25], v46 offset:128
	ds_read_b128 v[26:29], v46 offset:144
	v_lshlrev_b32_e32 v46, 2, v82
	v_or_b32_e32 v42, 2, v46
	s_waitcnt lgkmcnt(1)
	v_mov_b32_e32 v35, v24
	v_mov_b32_e32 v24, v23
	s_waitcnt lgkmcnt(0)
	v_mov_b32_e32 v37, v28
	v_mov_b32_e32 v28, v27
	v_mov_b32_e32 v34, v22
	v_pk_mul_f32 v[22:23], v[30:31], v[24:25]
	v_mov_b32_e32 v36, v26
	v_pk_mul_f32 v[26:27], v[32:33], v[28:29]
	v_pk_fma_f32 v[22:23], v[18:19], v[34:35], v[22:23] neg_lo:[0,0,1] neg_hi:[0,0,1]
	v_pk_fma_f32 v[26:27], v[20:21], v[36:37], v[26:27] neg_lo:[0,0,1] neg_hi:[0,0,1]
	v_cvt_pk_bf16_f32 v22, v22, v23
	v_cvt_pk_bf16_f32 v23, v26, v27
	v_pk_mul_f32 v[26:27], v[30:31], v[34:35]
	s_nop 0
	v_pk_fma_f32 v[18:19], v[18:19], v[24:25], v[26:27]
	v_pk_mul_f32 v[24:25], v[32:33], v[36:37]
	v_cvt_pk_bf16_f32 v18, v18, v19
	v_pk_fma_f32 v[20:21], v[20:21], v[28:29], v[24:25]
	v_bitop3_b32 v27, v81, v46, 4 bitop3:0x72
	v_cvt_pk_bf16_f32 v19, v20, v21
	v_add_u32_e32 v20, v47, v83
	ds_write_b64 v20, v[22:23]
	v_add_u32_e32 v20, v47, v94
	ds_write_b64 v20, v[18:19]
	v_and_b32_e32 v18, 0xfffffcf, v78
	v_mul_lo_u32 v18, v18, s10
	v_add_u32_e32 v26, 0, v18
	v_and_or_b32 v18, v46, 4, v81
	v_lshl_add_u32 v18, v18, 4, v26
	s_waitcnt lgkmcnt(0)
	s_barrier
	ds_read_b128 v[18:21], v18
	v_lshl_add_u32 v26, v27, 4, v26
	ds_read_b128 v[26:29], v26
	s_waitcnt vmcnt(3) lgkmcnt(1)
	v_mfma_f32_16x16x32_bf16 v[22:25], v[18:21], v[10:13], 0
	v_or_b32_e32 v47, 4, v81
	s_waitcnt vmcnt(1)
	v_mfma_f32_16x16x32_bf16 v[18:21], v[18:21], v[14:17], 0
	s_waitcnt lgkmcnt(0)
	v_mfma_f32_16x16x32_bf16 v[38:41], v[26:29], v[6:9], v[22:25]
	s_waitcnt vmcnt(0)
	v_mfma_f32_16x16x32_bf16 v[34:37], v[26:29], v[2:5], v[18:21]
	v_or_b32_e32 v26, 1, v46
	v_or_b32_e32 v46, 3, v46
	s_nop 1
	v_lshl_or_b32 v18, v26, 4, v80
	v_mul_lo_u32 v18, v18, s10
	v_add_u32_e32 v27, 0, v18
	v_bitop3_b32 v18, v26, v81, 5 bitop3:0x6c
	v_lshl_add_u32 v18, v18, 4, v27
	ds_read_b128 v[18:21], v18
	v_bitop3_b32 v26, v26, v47, 5 bitop3:0x6c
	v_lshl_add_u32 v26, v26, 4, v27
	ds_read_b128 v[26:29], v26
	s_waitcnt lgkmcnt(1)
	v_mfma_f32_16x16x32_bf16 v[22:25], v[18:21], v[10:13], 0
	v_mfma_f32_16x16x32_bf16 v[18:21], v[18:21], v[14:17], 0
	s_waitcnt lgkmcnt(0)
	v_mfma_f32_16x16x32_bf16 v[30:33], v[26:29], v[6:9], v[22:25]
	v_mfma_f32_16x16x32_bf16 v[26:29], v[26:29], v[2:5], v[18:21]
	s_nop 4
	v_lshl_or_b32 v18, v42, 4, v80
	v_mul_lo_u32 v18, v18, s10
	v_add_u32_e32 v43, 0, v18
	v_bitop3_b32 v18, v42, v81, 6 bitop3:0x6c
	v_lshl_add_u32 v18, v18, 4, v43
	ds_read_b128 v[18:21], v18
	v_bitop3_b32 v42, v42, v47, 6 bitop3:0x6c
	v_lshl_add_u32 v42, v42, 4, v43
	ds_read_b128 v[42:45], v42
	s_waitcnt lgkmcnt(1)
	v_mfma_f32_16x16x32_bf16 v[22:25], v[18:21], v[10:13], 0
	v_mfma_f32_16x16x32_bf16 v[18:21], v[18:21], v[14:17], 0
	s_waitcnt lgkmcnt(0)
	v_mfma_f32_16x16x32_bf16 v[22:25], v[42:45], v[6:9], v[22:25]
	v_mfma_f32_16x16x32_bf16 v[18:21], v[42:45], v[2:5], v[18:21]
	v_lshl_or_b32 v42, v46, 4, v80
	v_mul_lo_u32 v42, v42, s10
	v_add_u32_e32 v48, 0, v42
	v_bitop3_b32 v42, v46, v81, 7 bitop3:0x6c
	v_lshl_add_u32 v42, v42, 4, v48
	ds_read_b128 v[42:45], v42
	s_waitcnt lgkmcnt(0)
	v_mfma_f32_16x16x32_bf16 v[10:13], v[42:45], v[10:13], 0
	v_mfma_f32_16x16x32_bf16 v[14:17], v[42:45], v[14:17], 0
	v_bitop3_b32 v42, v46, v47, 7 bitop3:0x6c
	v_lshl_add_u32 v42, v42, 4, v48
	ds_read_b128 v[42:45], v42
	s_waitcnt lgkmcnt(0)
	v_mfma_f32_16x16x32_bf16 v[6:9], v[42:45], v[6:9], v[10:13]
	s_nop 2
	v_and_b32_e32 v13, 64, v1
	v_lshlrev_b32_e32 v10, 3, v82
	v_xor_b32_e32 v11, 16, v1
	v_add_u32_e32 v13, 64, v13
	v_add3_u32 v10, v10, s1, v79
	v_cmp_lt_i32_e32 vcc, v11, v13
	v_or_b32_e32 v10, v10, v76
	v_mfma_f32_16x16x32_bf16 v[2:5], v[42:45], v[2:5], v[14:17]
	v_cndmask_b32_e32 v11, v1, v11, vcc
	s_lshl_b32 s1, s7, 2
	v_bfe_u32 v12, v78, 4, 1
	v_lshlrev_b32_e32 v14, 2, v11
	v_pk_mul_f32 v[16:17], v[38:39], s[88:89] op_sel_hi:[1,0]
	v_pk_mul_f32 v[38:39], v[40:41], s[88:89] op_sel_hi:[1,0]
	v_ashrrev_i32_e32 v11, 31, v10
	v_cvt_pk_bf16_f32 v16, v16, v17
	v_cvt_pk_bf16_f32 v17, v38, v39
	v_lshlrev_b64 v[38:39], 11, v[10:11]
	s_add_u32 s22, s24, s1
	v_lshl_add_u64 v[38:39], s[84:85], 0, v[38:39]
	s_mov_b32 s1, s69
	v_lshl_add_u64 v[38:39], v[38:39], 0, s[0:1]
	v_lshlrev_b32_e32 v98, 3, v12
	v_lshl_add_u64 v[38:39], v[38:39], 0, v[98:99]
	s_mov_b32 s0, 0x1b00000
	v_add_co_u32_e32 v38, vcc, s0, v38
	v_and_b32_e32 v15, 0xffff0000, v16
	s_nop 0
	v_addc_co_u32_e32 v39, vcc, 0, v39, vcc
	global_store_dwordx2 v[38:39], v[16:17], off offset:1024
	v_lshlrev_b32_e32 v13, 16, v16
	v_mul_f32_e32 v15, v15, v15
	v_and_b32_e32 v16, 0xffff0000, v17
	v_fmac_f32_e32 v15, v13, v13
	v_lshlrev_b32_e32 v13, 16, v17
	v_mul_f32_e32 v16, v16, v16
	v_fmac_f32_e32 v16, v13, v13
	v_add_f32_e32 v13, v15, v16
	v_mov_b32_e32 v15, v13
	s_nop 1
	v_permlane16_swap_b32_e32 v13, v15
	v_cmp_eq_u32_e64 s[38:39], 0, v12
	s_addc_u32 s23, s25, 0
	s_and_saveexec_b64 s[0:1], s[38:39]
	s_cbranch_execz .LBB0_805
	v_lshlrev_b64 v[16:17], 7, v[10:11]
	s_waitcnt lgkmcnt(0)
	v_add_f32_e32 v13, v13, v15
	v_lshl_add_u64 v[16:17], s[22:23], 0, v[16:17]
	global_store_dword v[16:17], v13, off

.LBB0_821:
	s_cmpk_gt_i32 s49, 0xff
	s_mov_b64 s[0:1], -1
	s_cbranch_scc0 .LBB0_853
	s_add_i32 s0, s49, 0xffffff00
	s_lshr_b32 s68, s0, 2
	s_and_b32 s2, s49, 3
	s_lshl_b64 s[0:1], s[68:69], 8
	s_add_u32 s44, s0, 0x4000
	s_addc_u32 s45, s1, 0
	s_mul_i32 s0, s45, 0x600
	s_mul_hi_u32 s10, s44, 0x600
	s_add_i32 s10, s10, s0
	s_mul_i32 s11, s44, 0x600
	s_add_u32 s0, s84, s11
	s_addc_u32 s1, s85, s10
	s_mul_i32 s4, s2, 0x180
	s_add_u32 s0, s0, s4
	s_addc_u32 s1, s1, 0
	v_readlane_b32 s8, v251, 48
	v_readlane_b32 s9, v251, 49
	s_add_u32 s8, s8, s4
	s_addc_u32 s9, s9, 0
	s_lshl_b32 s4, s2, 8
	v_readlane_b32 s12, v253, 7
	v_mov_b32_e32 v166, v0
	v_readlane_b32 s13, v253, 8
	s_add_u32 s4, s12, s4
	s_addc_u32 s7, s13, 0
	v_ashrrev_i32_e32 v157, 6, v166
	v_and_b32_e32 v168, 31, v166
	v_and_b32_e32 v2, 0x3fffffc0, v166
	s_add_i32 s12, 0, 0x14000
	v_lshlrev_b32_e32 v156, 5, v157
	v_bfe_u32 v169, v166, 5, 1
	v_lshl_add_u32 v48, v2, 2, s12
	v_or_b32_e32 v4, v156, v168
	s_waitcnt lgkmcnt(0)
	v_mov_b64_e32 v[2:3], s[0:1]
	s_movk_i32 s12, 0x600
	v_mad_i64_i32 v[2:3], s[0:1], v4, s12, v[2:3]
	v_lshlrev_b32_e32 v46, 4, v169
	v_mov_b32_e32 v47, v99
	v_lshl_add_u64 v[8:9], v[2:3], 0, v[46:47]
	global_load_dwordx4 v[128:131], v[8:9], off
	global_load_dwordx4 v[124:127], v[8:9], off offset:32
	global_load_dwordx4 v[120:123], v[8:9], off offset:64
	global_load_dwordx4 v[116:119], v[8:9], off offset:96
	global_load_dwordx4 v[112:115], v[8:9], off offset:128
	global_load_dwordx4 v[108:111], v[8:9], off offset:160
	global_load_dwordx4 v[104:107], v[8:9], off offset:192
	global_load_dwordx4 v[100:103], v[8:9], off offset:224
	global_load_dwordx4 v[4:7], v[8:9], off offset:256
	global_load_dwordx4 v[132:135], v[8:9], off offset:288
	global_load_dwordx4 v[136:139], v[8:9], off offset:320
	global_load_dwordx4 v[140:143], v[8:9], off offset:352
	s_mov_b32 s100, 0xaaaaaaab
	v_lshrrev_b32_e32 v65, 6, v0
	v_lshl_add_u32 v66, v65, 7, v0
	v_mul_hi_u32 v67, v66, s100
	v_lshrrev_b32_e32 v67, 4, v67
	v_mul_u32_u24_e32 v68, 24, v67
	v_sub_u32_e32 v68, v66, v68
	v_and_b32_e32 v69, 7, v67
	v_xor_b32_e32 v68, v68, v69
	v_mul_u32_u24_e32 v69, 0x600, v67
	v_lshl_add_u32 v62, v68, 4, v69
	v_add_u32_e32 v66, 64, v66
	v_mul_hi_u32 v67, v66, s100
	v_lshrrev_b32_e32 v67, 4, v67
	v_mul_u32_u24_e32 v68, 24, v67
	v_sub_u32_e32 v68, v66, v68
	v_and_b32_e32 v69, 7, v67
	v_xor_b32_e32 v68, v68, v69
	v_mul_u32_u24_e32 v69, 0x600, v67
	v_lshl_add_u32 v63, v68, 4, v69
	v_add_u32_e32 v66, 64, v66
	v_mul_hi_u32 v67, v66, s100
	v_lshrrev_b32_e32 v67, 4, v67
	v_mul_u32_u24_e32 v68, 24, v67
	v_sub_u32_e32 v68, v66, v68
	v_and_b32_e32 v69, 7, v67
	v_xor_b32_e32 v68, v68, v69
	v_mul_u32_u24_e32 v69, 0x600, v67
	v_lshl_add_u32 v64, v68, 4, v69
	v_lshl_add_u32 v66, v65, 6, v0
	v_and_b32_e32 v67, 3, v66
	v_lshlrev_b32_e32 v67, 4, v67
	v_bfe_u32 v68, v66, 5, 2
	v_lshl_or_b32 v67, v68, 6, v67
	v_bfe_u32 v68, v66, 2, 2
	v_lshl_or_b32 v67, v68, 10, v67
	v_bfe_u32 v68, v66, 7, 1
	v_lshl_or_b32 v67, v68, 12, v67
	v_bfe_u32 v68, v66, 4, 1
	v_lshl_or_b32 v67, v68, 13, v67
	v_bfe_u32 v68, v66, 8, 2
	v_lshl_or_b32 v60, v68, 14, v67
	v_add_u32_e32 v66, 64, v66
	v_and_b32_e32 v67, 3, v66
	v_lshlrev_b32_e32 v67, 4, v67
	v_bfe_u32 v68, v66, 5, 2
	v_lshl_or_b32 v67, v68, 6, v67
	v_bfe_u32 v68, v66, 2, 2
	v_lshl_or_b32 v67, v68, 10, v67
	v_bfe_u32 v68, v66, 7, 1
	v_lshl_or_b32 v67, v68, 12, v67
	v_bfe_u32 v68, v66, 4, 1
	v_lshl_or_b32 v67, v68, 13, v67
	v_bfe_u32 v68, v66, 8, 2
	v_lshl_or_b32 v61, v68, 14, v67
	v_readfirstlane_b32 s101, v65
	s_nop 1
	s_mul_i32 vcc_lo, s101, 0xc00
	s_lshl_b32 vcc_hi, s101, 11
	s_lshl_b64 s[100:101], s[44:45], 10
	s_add_u32 s100, s4, s100
	s_addc_u32 s101, s7, s101
	s_add_u32 s14, s8, s11
	s_addc_u32 s15, s9, s10
	s_add_i32 m0, vcc_hi, 0x0
	s_nop 0
	global_load_lds_dwordx4 v60, s[100:101]
	s_add_i32 m0, vcc_hi, 0x400
	s_nop 0
	global_load_lds_dwordx4 v61, s[100:101]
	s_add_i32 m0, vcc_lo, 0x8000
	s_nop 0
	global_load_lds_dwordx4 v62, s[14:15]
	s_add_i32 m0, vcc_lo, 0x8400
	s_nop 0
	global_load_lds_dwordx4 v63, s[14:15]
	s_add_i32 m0, vcc_lo, 0x8800
	s_nop 0
	global_load_lds_dwordx4 v64, s[14:15]
	s_add_u32 s100, s100, 0x10000
	s_addc_u32 s101, s101, 0
	s_add_u32 s14, s14, 0x18000
	s_addc_u32 s15, s15, 0
	s_add_i32 m0, vcc_hi, 0x4000
	s_nop 0
	global_load_lds_dwordx4 v60, s[100:101]
	s_add_i32 m0, vcc_hi, 0x4400
	s_nop 0
	global_load_lds_dwordx4 v61, s[100:101]
	s_add_i32 m0, vcc_lo, 0xe000
	s_nop 0
	global_load_lds_dwordx4 v62, s[14:15]
	s_add_i32 m0, vcc_lo, 0xe400
	s_nop 0
	global_load_lds_dwordx4 v63, s[14:15]
	s_add_i32 m0, vcc_lo, 0xe800
	s_nop 0
	global_load_lds_dwordx4 v64, s[14:15]
	v_lshlrev_b32_e32 v2, 12, v157
	s_add_i32 s0, 0, 0x14800
	v_lshlrev_b32_e32 v3, 7, v168
	v_add3_u32 v35, s0, v2, v3
	v_bitop3_b32 v3, v169, v166, 7 bitop3:0x78
	v_lshl_add_u32 v3, v3, 4, v35
	v_lshlrev_b32_e32 v2, 4, v166
	v_and_b32_e32 v34, 0x70, v2
	s_movk_i32 s0, 0x60
	s_movk_i32 s16, 0x180
	v_and_b32_e32 v167, 63, v166
	s_cmp_lg_u32 0, -1
	v_mul_u32_u24_e32 v39, 0x180, v168
	v_or_b32_e32 v36, 32, v46
	v_bitop3_b32 v40, v36, v39, v34 bitop3:0xde
	v_add_u32_e32 v178, 0, v40
	v_or_b32_e32 v37, 64, v46
	v_or_b32_e32 v38, 0x60, v46
	v_cmp_gt_u32_e64 s[40:41], 32, v167
	v_lshl_add_u32 v175, v168, 2, v48
	v_add_u32_e32 v174, v48, v46
	s_waitcnt vmcnt(10)
	ds_write_b128 v3, v[4:7]
	v_bitop3_b32 v3, v46, v34, 32 bitop3:0x36
	v_add_u32_e32 v172, v35, v3
	v_bitop3_b32 v3, v46, v34, 64 bitop3:0x36
	v_add_u32_e32 v173, v35, v3
	v_bitop3_b32 v3, v46, v34, s0 bitop3:0x36
	v_add_u32_e32 v171, v35, v3
	v_ashrrev_i32_e32 v3, 4, v166
	s_mov_b32 s0, 0x2aaaaaab
	ds_write_b128 v172, v[132:135]
	ds_write_b128 v173, v[136:139]
	v_and_b32_e32 v8, 3, v3
	ds_write_b128 v171, v[140:143]
	v_and_b32_e32 v6, 0xfffff0, v3
	v_lshlrev_b32_e32 v7, 1, v3
	v_and_or_b32 v6, v7, 8, v6
	v_lshrrev_b32_e32 v7, 1, v3
	v_and_or_b32 v7, v7, 4, v8
	v_add_u32_e32 v8, 32, v3
	v_and_b32_e32 v9, 0xfffff0, v8
	v_lshlrev_b32_e32 v8, 1, v8
	v_lshlrev_b32_e32 v4, 3, v166
	v_and_or_b32 v8, v8, 8, v9
	v_and_b32_e32 v5, 0x78, v4
	v_lshrrev_b32_e32 v6, 1, v6
	v_bfe_u32 v4, v4, 5, 2
	v_lshrrev_b32_e32 v8, 1, v8
	v_or_b32_e32 v6, v6, v4
	v_or_b32_e32 v4, v8, v4
	v_mul_hi_i32 v8, v166, s0
	v_lshrrev_b32_e32 v9, 31, v8
	v_ashrrev_i32_e32 v8, 2, v8
	v_add_u32_e32 v8, v8, v9
	v_mul_lo_u32 v9, v8, 24
	v_sub_u32_e32 v9, v166, v9
	v_mul_lo_u32 v10, v8, s12
	v_lshl_add_u32 v158, v9, 4, v10
	v_mul_lo_u32 v10, v8, s16
	v_bitop3_b32 v8, v8, v9, 7 bitop3:0x6c
	v_lshl_add_u32 v24, v8, 4, v10
	v_add_u32_e32 v8, 0x200, v166
	v_mul_hi_i32 v9, v8, s0
	v_lshrrev_b32_e32 v10, 31, v9
	v_ashrrev_i32_e32 v9, 2, v9
	v_add_u32_e32 v9, v9, v10
	v_mul_lo_u32 v10, v9, 24
	v_sub_u32_e32 v8, v8, v10
	v_mul_lo_u32 v10, v9, s12
	v_lshl_add_u32 v160, v8, 4, v10
	v_mul_lo_u32 v10, v9, s16
	v_bitop3_b32 v8, v9, v8, 7 bitop3:0x6c
	v_lshl_add_u32 v25, v8, 4, v10
	v_add_u32_e32 v8, 0x400, v166
	v_mul_hi_i32 v9, v8, s0
	v_lshrrev_b32_e32 v10, 31, v9
	v_ashrrev_i32_e32 v9, 2, v9
	v_add_u32_e32 v9, v9, v10
	v_mul_lo_u32 v10, v9, 24
	v_sub_u32_e32 v8, v8, v10
	v_mul_lo_u32 v10, v9, s12
	v_lshlrev_b32_e32 v5, 1, v5
	v_lshl_add_u32 v162, v8, 4, v10
	v_mul_lo_u32 v10, v9, s16
	v_bitop3_b32 v8, v9, v8, 7 bitop3:0x6c
	v_lshlrev_b32_e32 v7, 6, v7
	v_lshlrev_b32_e32 v4, 9, v4
	v_lshl_add_u32 v26, v8, 4, v10
	v_and_b32_e32 v8, 48, v5
	v_or3_b32 v28, v4, v7, v8
	v_lshl_or_b32 v98, v3, 10, v5
	v_lshlrev_b32_e32 v3, 3, v167
	v_and_b32_e32 v4, 0xc0, v2
	v_lshlrev_b32_e32 v5, 1, v166
	v_and_or_b32 v4, v3, 24, v4
	v_and_b32_e32 v5, 32, v5
	v_and_b32_e32 v3, 0x100, v3
	v_or3_b32 v152, v4, v5, v3
	s_cselect_b32 s0, 0, 0
	v_add_u32_e32 v170, s0, v152
	s_lshl_b64 s[0:1], s[44:45], 10
	s_add_u32 s12, s4, s0
	s_addc_u32 s13, s7, s1
	v_lshlrev_b32_e32 v6, 9, v6
	s_add_u32 s14, s8, s11
	v_or3_b32 v27, v6, v7, v8
	v_add_u32_e32 v164, 0x8000, v98
	s_addc_u32 s15, s9, s10
	s_movk_i32 s10, 0x70
	v_bitop3_b32 v45, v46, v2, s10 bitop3:0x78
	v_bitop3_b32 v2, v46, v39, v34 bitop3:0xde
	v_add_u32_e32 v214, 0, v27
	v_add_u32_e32 v215, 0, v28
	v_add_u32_e32 v216, 0, v24
	v_add_u32_e32 v217, 0, v25
	v_add_u32_e32 v218, 0, v26
	v_mov_b32_e32 v3, 0x3000
	v_add_u32_e32 v176, 0, v2
	v_mad_u32_u24 v44, v168, s16, v3
	v_bitop3_b32 v179, v36, v44, v34 bitop3:0xde
	v_bitop3_b32 v36, v37, v39, v34 bitop3:0xde
	v_add_u32_e32 v180, 0, v36
	v_bitop3_b32 v36, v38, v39, v34 bitop3:0xde
	v_add_u32_e32 v182, 0, v36
	v_bitop3_b32 v181, v37, v44, v34 bitop3:0xde
	v_bitop3_b32 v183, v38, v44, v34 bitop3:0xde
	s_movk_i32 s10, 0x80
	v_add_u32_e32 v194, v35, v45
	v_bitop3_b32 v177, v46, v44, v34 bitop3:0xde
	s_mul_i32 s15, s68, 0x60000
	s_mul_hi_u32 s14, s68, 0x60000
	s_waitcnt vmcnt(5) lgkmcnt(0)
	s_barrier
	ds_read_b128 v[2:5], v176 offset:32768
	ds_read_b128 v[6:9], v176 offset:45056
	ds_read_b128 v[40:43], v178 offset:32768
	ds_read_b128 v[50:53], v178 offset:45056
	s_waitcnt lgkmcnt(3)
	v_mfma_f32_32x32x16_bf16 v[18:33], v[2:5], v[128:131], 0
	ds_read_b128 v[36:39], v182 offset:45056
	s_waitcnt lgkmcnt(3)
	v_mfma_f32_32x32x16_bf16 v[2:17], v[6:9], v[128:131], 0
	s_waitcnt lgkmcnt(2)
	v_mfma_f32_32x32x16_bf16 v[18:33], v[40:43], v[124:127], v[18:33]
	ds_read_b128 v[40:43], v180 offset:32768
	s_waitcnt lgkmcnt(2)
	v_mfma_f32_32x32x16_bf16 v[2:17], v[50:53], v[124:127], v[2:17]
	ds_read_b128 v[50:53], v180 offset:45056
	s_waitcnt lgkmcnt(1)
	v_mfma_f32_32x32x16_bf16 v[18:33], v[40:43], v[120:123], v[18:33]
	ds_read_b128 v[40:43], v182 offset:32768
	s_waitcnt lgkmcnt(1)
	v_mfma_f32_32x32x16_bf16 v[2:17], v[50:53], v[120:123], v[2:17]
	ds_read_b128 v[50:53], v194
	s_waitcnt lgkmcnt(1)
	v_mfma_f32_32x32x16_bf16 v[18:33], v[40:43], v[116:119], v[18:33]
	v_bitop3_b32 v40, v46, v34, s10 bitop3:0x36
	v_add_u32_e32 v185, v40, v44
	s_movk_i32 s10, 0xa0
	v_mfma_f32_32x32x16_bf16 v[2:17], v[36:39], v[116:119], v[2:17]
	v_mad_u32_u24 v36, v168, s16, v40
	v_add_u32_e32 v184, 0, v36
	ds_read_b128 v[36:39], v184 offset:32768
	ds_read_b128 v[40:43], v184 offset:45056
	s_waitcnt lgkmcnt(0)
	v_mfma_f32_32x32x16_bf16 v[2:17], v[40:43], v[112:115], v[2:17]
	v_bitop3_b32 v40, v46, v34, s10 bitop3:0x36
	v_add_u32_e32 v187, v40, v44
	s_movk_i32 s10, 0xc0
	v_mfma_f32_32x32x16_bf16 v[18:33], v[36:39], v[112:115], v[18:33]
	v_mad_u32_u24 v36, v168, s16, v40
	v_add_u32_e32 v186, 0, v36
	ds_read_b128 v[36:39], v186 offset:32768
	ds_read_b128 v[40:43], v186 offset:45056
	s_waitcnt lgkmcnt(0)
	v_mfma_f32_32x32x16_bf16 v[2:17], v[40:43], v[108:111], v[2:17]
	v_bitop3_b32 v40, v46, v34, s10 bitop3:0x36
	v_add_u32_e32 v189, v40, v44
	s_movk_i32 s10, 0xe0
	v_mfma_f32_32x32x16_bf16 v[18:33], v[36:39], v[108:111], v[18:33]
	v_mad_u32_u24 v36, v168, s16, v40
	v_add_u32_e32 v188, 0, v36
	ds_read_b128 v[36:39], v188 offset:32768
	ds_read_b128 v[40:43], v188 offset:45056
	s_waitcnt lgkmcnt(0)
	v_mfma_f32_32x32x16_bf16 v[2:17], v[40:43], v[104:107], v[2:17]
	v_bitop3_b32 v40, v46, v34, s10 bitop3:0x36
	v_add_u32_e32 v191, v40, v44
	s_movk_i32 s10, 0x120
	v_bitop3_b32 v35, v46, v34, s10 bitop3:0x36
	s_movk_i32 s10, 0x140
	v_add_u32_e32 v196, v35, v44
	v_mfma_f32_32x32x16_bf16 v[18:33], v[36:39], v[104:107], v[18:33]
	v_mad_u32_u24 v36, v168, s16, v40
	v_add_u32_e32 v190, 0, v36
	ds_read_b128 v[36:39], v190 offset:32768
	ds_read_b128 v[40:43], v190 offset:45056
	s_waitcnt lgkmcnt(0)
	v_mfma_f32_32x32x16_bf16 v[2:17], v[40:43], v[100:103], v[2:17]
	v_bitop3_b32 v40, v46, v34, s82 bitop3:0x36
	v_add_u32_e32 v193, v40, v44
	v_mfma_f32_32x32x16_bf16 v[18:33], v[36:39], v[100:103], v[18:33]
	v_mad_u32_u24 v36, v168, s16, v40
	v_add_u32_e32 v192, 0, v36
	ds_read_b128 v[36:39], v192 offset:32768
	ds_read_b128 v[40:43], v192 offset:45056
	s_waitcnt lgkmcnt(1)
	v_mfma_f32_32x32x16_bf16 v[18:33], v[36:39], v[50:53], v[18:33]
	v_mad_u32_u24 v36, v168, s16, v35
	v_add_u32_e32 v195, 0, v36
	ds_read_b128 v[36:39], v195 offset:32768
	v_bitop3_b32 v35, v46, v34, s10 bitop3:0x36
	s_movk_i32 s10, 0x160
	v_bitop3_b32 v34, v46, v34, s10 bitop3:0x36
	v_add_u32_e32 v198, v35, v44
	s_waitcnt lgkmcnt(1)
	v_mfma_f32_32x32x16_bf16 v[2:17], v[40:43], v[50:53], v[2:17]
	ds_read_b128 v[40:43], v195 offset:45056
	ds_read_b128 v[50:53], v172
	v_add_u32_e32 v213, v34, v44
	s_waitcnt lgkmcnt(0)
	v_mfma_f32_32x32x16_bf16 v[18:33], v[36:39], v[50:53], v[18:33]
	v_mad_u32_u24 v36, v168, s16, v35
	v_add_u32_e32 v197, 0, v36
	ds_read_b128 v[36:39], v197 offset:32768
	v_mad_u32_u24 v35, v168, s16, v34
	v_add_u32_e32 v199, 0, v35
	v_mfma_f32_32x32x16_bf16 v[2:17], v[40:43], v[50:53], v[2:17]
	ds_read_b128 v[40:43], v197 offset:45056
	ds_read_b128 v[50:53], v173
	s_waitcnt lgkmcnt(0)
	v_mfma_f32_32x32x16_bf16 v[18:33], v[36:39], v[50:53], v[18:33]
	v_mfma_f32_32x32x16_bf16 v[2:17], v[40:43], v[50:53], v[2:17]
	ds_read_b128 v[38:41], v199 offset:32768
	ds_read_b128 v[34:37], v199 offset:45056
	ds_read_b128 v[42:45], v171
	s_waitcnt lgkmcnt(0)
	v_mfma_f32_32x32x16_bf16 v[18:33], v[38:41], v[42:45], v[18:33]
	v_mfma_f32_32x32x16_bf16 v[2:17], v[34:37], v[42:45], v[2:17]
	s_nop 10
	v_max_f32_e32 v34, v19, v19
	v_max_f32_e32 v35, v18, v18
	v_max_f32_e32 v34, v35, v34
	v_max3_f32 v34, v34, v20, v21
	v_max3_f32 v34, v34, v22, v23
	v_max3_f32 v34, v34, v24, v25
	v_max3_f32 v34, v34, v26, v27
	v_max3_f32 v34, v34, v28, v29
	v_max3_f32 v34, v34, v30, v31
	v_max3_f32 v34, v34, v32, v33
	v_max3_f32 v34, v34, v2, v3
	v_max3_f32 v34, v34, v4, v5
	v_max3_f32 v34, v34, v6, v7
	v_max3_f32 v34, v34, v8, v9
	v_max3_f32 v34, v34, v10, v11
	v_max3_f32 v34, v34, v12, v13
	v_max3_f32 v34, v34, v14, v15
	v_max3_f32 v34, v34, v16, v17
	v_mov_b32_e32 v35, v34
	s_nop 1
	v_permlane32_swap_b32_e32 v34, v35
	v_max_f32_e32 v35, v35, v35
	v_max_f32_e32 v34, v34, v34
	v_max_f32_e32 v34, v34, v35
	v_add_f32_e32 v35, 0x7149f2ca, v34
	v_cmp_ge_f32_e32 vcc, s5, v35
	s_cmp_eq_u64 vcc, exec
	s_cselect_b64 s[38:39], -1, 0
	s_lshl_b64 s[10:11], s[68:69], 18
	s_add_u32 s10, s4, s10
	s_addc_u32 s11, s7, s11
	s_add_u32 s12, s10, 0x1010000
	v_max_f32_e32 v154, 0xf149f2ca, v34
	v_mov_b32_e32 v34, 0xf149f2ca
	s_addc_u32 s13, s11, 0
	v_cndmask_b32_e64 v153, v154, v34, s[38:39]
	s_add_u32 s8, s8, s15
	v_mul_f32_e32 v38, 0xbdd53b94, v153
	s_addc_u32 s9, s9, s14
	v_fmamk_f32 v18, v18, 0x3dd53b94, v38
	v_fmamk_f32 v19, v19, 0x3dd53b94, v38
	v_fmamk_f32 v20, v20, 0x3dd53b94, v38
	v_fmamk_f32 v21, v21, 0x3dd53b94, v38
	s_add_u32 s14, s8, 0x1818000
	v_fmamk_f32 v22, v22, 0x3dd53b94, v38
	v_fmamk_f32 v23, v23, 0x3dd53b94, v38
	v_fmamk_f32 v24, v24, 0x3dd53b94, v38
	v_fmamk_f32 v25, v25, 0x3dd53b94, v38
	v_fmamk_f32 v26, v26, 0x3dd53b94, v38
	v_fmamk_f32 v27, v27, 0x3dd53b94, v38
	v_fmamk_f32 v28, v28, 0x3dd53b94, v38
	v_fmamk_f32 v29, v29, 0x3dd53b94, v38
	v_fmamk_f32 v56, v30, 0x3dd53b94, v38
	v_fmamk_f32 v57, v31, 0x3dd53b94, v38
	v_fmamk_f32 v58, v32, 0x3dd53b94, v38
	v_fmamk_f32 v59, v33, 0x3dd53b94, v38
	v_fmamk_f32 v51, v2, 0x3dd53b94, v38
	v_fmamk_f32 v52, v3, 0x3dd53b94, v38
	v_fmamk_f32 v53, v4, 0x3dd53b94, v38
	v_fmamk_f32 v54, v5, 0x3dd53b94, v38
	v_fmamk_f32 v55, v6, 0x3dd53b94, v38
	v_fmamk_f32 v42, v7, 0x3dd53b94, v38
	v_fmamk_f32 v43, v8, 0x3dd53b94, v38
	v_fmamk_f32 v44, v9, 0x3dd53b94, v38
	v_fmamk_f32 v45, v10, 0x3dd53b94, v38
	v_fmamk_f32 v47, v11, 0x3dd53b94, v38
	v_fmamk_f32 v49, v12, 0x3dd53b94, v38
	v_fmamk_f32 v50, v13, 0x3dd53b94, v38
	v_fmamk_f32 v39, v14, 0x3dd53b94, v38
	v_fmamk_f32 v40, v15, 0x3dd53b94, v38
	v_fmamk_f32 v41, v16, 0x3dd53b94, v38
	v_fmac_f32_e32 v38, 0x3dd53b94, v17
	v_exp_f32_e32 v31, v18
	v_exp_f32_e32 v33, v19
	v_exp_f32_e32 v34, v20
	v_exp_f32_e32 v35, v21
	s_addc_u32 s15, s9, 0
	v_exp_f32_e32 v36, v22
	v_exp_f32_e32 v37, v23
	v_exp_f32_e32 v30, v24
	v_exp_f32_e32 v32, v25
	v_exp_f32_e32 v25, v26
	v_exp_f32_e32 v27, v27
	v_exp_f32_e32 v28, v28
	v_exp_f32_e32 v29, v29
	v_exp_f32_e32 v22, v56
	v_exp_f32_e32 v23, v57
	v_exp_f32_e32 v24, v58
	v_exp_f32_e32 v26, v59
	s_add_i32 s12, 0, 0xe000
	v_add_u32_e32 v6, s12, v177
	v_add_u32_e32 v10, s12, v179
	v_add_u32_e32 v11, s12, v181
	v_add_u32_e32 v12, s12, v183
	v_add_u32_e32 v13, s12, v185
	v_add_u32_e32 v14, s12, v187
	v_add_u32_e32 v15, s12, v189
	v_add_u32_e32 v16, s12, v191
	v_add_u32_e32 v17, s12, v193
	v_add_u32_e32 v18, s12, v196
	v_add_u32_e32 v19, s12, v198
	v_add_u32_e32 v20, s12, v213
	s_waitcnt vmcnt(0) lgkmcnt(0)
	s_barrier
	ds_read_b128 v[2:5], v176 offset:57344
	ds_read_b128 v[6:9], v6
	v_cvt_pk_bf16_f32 v204, v25, v27
	v_cvt_pk_bf16_f32 v205, v28, v29
	v_cvt_pk_bf16_f32 v206, v22, v23
	s_waitcnt lgkmcnt(1)
	v_mfma_f32_32x32x16_bf16 v[82:97], v[2:5], v[128:131], 0
	v_cvt_pk_bf16_f32 v207, v24, v26
	v_permlane32_swap_b32_e32 v204, v206
	s_nop 0
	v_permlane32_swap_b32_e32 v205, v207
	s_waitcnt lgkmcnt(0)
	v_mfma_f32_32x32x16_bf16 v[66:81], v[6:9], v[128:131], 0
	ds_read_b128 v[2:5], v178 offset:57344
	ds_read_b128 v[6:9], v10
	s_waitcnt lgkmcnt(1)
	v_mfma_f32_32x32x16_bf16 v[82:97], v[2:5], v[124:127], v[82:97]
	s_waitcnt lgkmcnt(0)
	v_mfma_f32_32x32x16_bf16 v[66:81], v[6:9], v[124:127], v[66:81]
	ds_read_b128 v[2:5], v180 offset:57344
	ds_read_b128 v[6:9], v11
	s_waitcnt lgkmcnt(1)
	v_mfma_f32_32x32x16_bf16 v[82:97], v[2:5], v[120:123], v[82:97]
	s_waitcnt lgkmcnt(0)
	v_mfma_f32_32x32x16_bf16 v[66:81], v[6:9], v[120:123], v[66:81]
	ds_read_b128 v[2:5], v182 offset:57344
	ds_read_b128 v[6:9], v12
	s_waitcnt lgkmcnt(1)
	v_mfma_f32_32x32x16_bf16 v[82:97], v[2:5], v[116:119], v[82:97]
	s_waitcnt lgkmcnt(0)
	v_mfma_f32_32x32x16_bf16 v[66:81], v[6:9], v[116:119], v[66:81]
	ds_read_b128 v[2:5], v184 offset:57344
	ds_read_b128 v[6:9], v13
	s_waitcnt lgkmcnt(1)
	v_mfma_f32_32x32x16_bf16 v[82:97], v[2:5], v[112:115], v[82:97]
	s_waitcnt lgkmcnt(0)
	v_mfma_f32_32x32x16_bf16 v[66:81], v[6:9], v[112:115], v[66:81]
	ds_read_b128 v[2:5], v186 offset:57344
	ds_read_b128 v[6:9], v14
	v_exp_f32_e32 v14, v39
	s_waitcnt lgkmcnt(1)
	v_mfma_f32_32x32x16_bf16 v[82:97], v[2:5], v[108:111], v[82:97]
	s_waitcnt lgkmcnt(0)
	v_mfma_f32_32x32x16_bf16 v[66:81], v[6:9], v[108:111], v[66:81]
	ds_read_b128 v[2:5], v188 offset:57344
	ds_read_b128 v[6:9], v15
	v_exp_f32_e32 v15, v40
	s_nop 0
	v_cvt_pk_bf16_f32 v224, v14, v15
	s_waitcnt lgkmcnt(1)
	v_mfma_f32_32x32x16_bf16 v[82:97], v[2:5], v[104:107], v[82:97]
	s_waitcnt lgkmcnt(0)
	v_mfma_f32_32x32x16_bf16 v[66:81], v[6:9], v[104:107], v[66:81]
	ds_read_b128 v[2:5], v190 offset:57344
	ds_read_b128 v[6:9], v16
	v_exp_f32_e32 v16, v41
	s_waitcnt lgkmcnt(1)
	v_mfma_f32_32x32x16_bf16 v[82:97], v[2:5], v[100:103], v[82:97]
	s_waitcnt lgkmcnt(0)
	v_mfma_f32_32x32x16_bf16 v[66:81], v[6:9], v[100:103], v[66:81]
	ds_read_b128 v[2:5], v192 offset:57344
	ds_read_b128 v[6:9], v17
	ds_read_b128 v[10:13], v194
	v_exp_f32_e32 v17, v38
	s_nop 0
	v_cvt_pk_bf16_f32 v225, v16, v17
	s_waitcnt lgkmcnt(0)
	v_mfma_f32_32x32x16_bf16 v[82:97], v[2:5], v[10:13], v[82:97]
	v_mfma_f32_32x32x16_bf16 v[66:81], v[6:9], v[10:13], v[66:81]
	ds_read_b128 v[2:5], v195 offset:57344
	ds_read_b128 v[6:9], v18
	ds_read_b128 v[10:13], v172
	v_add_f32_e32 v18, 0, v31
	v_add_f32_e32 v18, v33, v18
	v_add_f32_e32 v18, v34, v18
	v_add_f32_e32 v18, v35, v18
	v_add_f32_e32 v18, v36, v18
	v_add_f32_e32 v18, v37, v18
	s_waitcnt lgkmcnt(0)
	v_mfma_f32_32x32x16_bf16 v[82:97], v[2:5], v[10:13], v[82:97]
	v_add_f32_e32 v18, v30, v18
	v_add_f32_e32 v18, v32, v18
	v_add_f32_e32 v18, v25, v18
	v_add_f32_e32 v18, v27, v18
	v_add_f32_e32 v18, v28, v18
	v_add_f32_e32 v18, v29, v18
	v_add_f32_e32 v18, v22, v18
	v_mfma_f32_32x32x16_bf16 v[66:81], v[6:9], v[10:13], v[66:81]
	ds_read_b128 v[2:5], v197 offset:57344
	ds_read_b128 v[6:9], v19
	ds_read_b128 v[10:13], v173
	v_add_f32_e32 v18, v23, v18
	v_add_f32_e32 v18, v24, v18
	v_add_f32_e32 v18, v26, v18
	s_waitcnt lgkmcnt(0)
	v_mfma_f32_32x32x16_bf16 v[82:97], v[2:5], v[10:13], v[82:97]
	v_mfma_f32_32x32x16_bf16 v[66:81], v[6:9], v[10:13], v[66:81]
	ds_read_b128 v[2:5], v199 offset:57344
	ds_read_b128 v[6:9], v20
	ds_read_b128 v[10:13], v171
	s_waitcnt lgkmcnt(0)
	v_mfma_f32_32x32x16_bf16 v[82:97], v[2:5], v[10:13], v[82:97]
	v_exp_f32_e32 v2, v51
	v_exp_f32_e32 v3, v52
	v_exp_f32_e32 v4, v53
	v_exp_f32_e32 v5, v54
	v_add_f32_e32 v18, v2, v18
	v_add_f32_e32 v18, v3, v18
	v_add_f32_e32 v18, v4, v18
	v_mfma_f32_32x32x16_bf16 v[66:81], v[6:9], v[10:13], v[66:81]
	v_exp_f32_e32 v6, v55
	v_exp_f32_e32 v7, v42
	v_exp_f32_e32 v8, v43
	v_exp_f32_e32 v9, v44
	v_add_f32_e32 v18, v5, v18
	v_exp_f32_e32 v10, v45
	v_add_f32_e32 v18, v6, v18
	v_exp_f32_e32 v11, v47
	v_add_f32_e32 v18, v7, v18
	v_exp_f32_e32 v12, v49
	v_add_f32_e32 v18, v8, v18
	v_exp_f32_e32 v13, v50
	v_add_f32_e32 v18, v9, v18
	v_add_f32_e32 v18, v10, v18
	v_add_f32_e32 v18, v11, v18
	v_add_f32_e32 v18, v12, v18
	v_add_f32_e32 v18, v13, v18
	v_add_f32_e32 v18, v14, v18
	v_add_f32_e32 v18, v15, v18
	v_add_f32_e32 v18, v16, v18
	v_add_f32_e32 v219, v17, v18
	v_mov_b32_e32 v220, v219
	v_cvt_pk_bf16_f32 v50, v31, v33
	v_cvt_pk_bf16_f32 v51, v34, v35
	v_cvt_pk_bf16_f32 v52, v36, v37
	v_cvt_pk_bf16_f32 v53, v30, v32
	v_permlane32_swap_b32_e32 v219, v220
	v_permlane32_swap_b32_e32 v50, v52
	v_permlane32_swap_b32_e32 v51, v53
	v_cvt_pk_bf16_f32 v208, v2, v3
	v_cvt_pk_bf16_f32 v209, v4, v5
	v_cvt_pk_bf16_f32 v210, v6, v7
	v_cvt_pk_bf16_f32 v211, v8, v9
	v_cvt_pk_bf16_f32 v222, v10, v11
	v_cvt_pk_bf16_f32 v223, v12, v13
	v_permlane32_swap_b32_e32 v208, v210
	v_permlane32_swap_b32_e32 v209, v211
	v_permlane32_swap_b32_e32 v222, v224
	v_permlane32_swap_b32_e32 v223, v225
	s_add_u32 s10, s10, 0x1020000
	s_addc_u32 s11, s11, 0
	s_add_u32 s22, s8, 0x1830000
	s_addc_u32 s23, s9, 0
	global_load_dwordx4 v[132:135], v164, s[10:11]
	global_load_dwordx4 v[136:139], v158, s[22:23]
	global_load_dwordx4 v[140:143], v160, s[22:23]
	global_load_dwordx4 v[148:151], v98, s[10:11]
	global_load_dwordx4 v[144:147], v162, s[22:23]
	ds_read_b64_tr_b16 v[2:3], v170 offset:0
	ds_read_b64_tr_b16 v[4:5], v170 offset:0x800
	ds_read_b64_tr_b16 v[18:19], v170 offset:0x1000
	ds_read_b64_tr_b16 v[20:21], v170 offset:0x1800
	ds_read_b64_tr_b16 v[22:23], v170 offset:0x2000
	ds_read_b64_tr_b16 v[24:25], v170 offset:0x2800
	ds_read_b64_tr_b16 v[26:27], v170 offset:0x3000
	ds_read_b64_tr_b16 v[28:29], v170 offset:0x3800
	s_waitcnt lgkmcnt(0)
	s_nop 0
	v_mfma_f32_32x32x16_bf16 v[2:17], v[50:53], v[2:5], 0
	v_mfma_f32_32x32x16_bf16 v[2:17], v[204:207], v[18:21], v[2:17]
	ds_read_b64_tr_b16 v[18:19], v170 offset:0x200
	ds_read_b64_tr_b16 v[20:21], v170 offset:0xa00
	ds_read_b64_tr_b16 v[34:35], v170 offset:0x1200
	ds_read_b64_tr_b16 v[36:37], v170 offset:0x1a00
	ds_read_b64_tr_b16 v[38:39], v170 offset:0x2200
	ds_read_b64_tr_b16 v[40:41], v170 offset:0x2a00
	ds_read_b64_tr_b16 v[42:43], v170 offset:0x3200
	v_mfma_f32_32x32x16_bf16 v[2:17], v[208:211], v[22:25], v[2:17]
	ds_read_b64_tr_b16 v[44:45], v170 offset:0x3a00
	s_waitcnt lgkmcnt(0)
	v_mfma_f32_32x32x16_bf16 v[2:17], v[222:225], v[26:29], v[2:17]
	v_mfma_f32_32x32x16_bf16 v[18:33], v[50:53], v[18:21], 0
	v_mfma_f32_32x32x16_bf16 v[18:33], v[204:207], v[34:37], v[18:33]
	ds_read_b64_tr_b16 v[34:35], v170 offset:0x400
	ds_read_b64_tr_b16 v[36:37], v170 offset:0xc00
	ds_read_b64_tr_b16 v[54:55], v170 offset:0x1400
	ds_read_b64_tr_b16 v[56:57], v170 offset:0x1c00
	ds_read_b64_tr_b16 v[58:59], v170 offset:0x2400
	ds_read_b64_tr_b16 v[60:61], v170 offset:0x2c00
	ds_read_b64_tr_b16 v[62:63], v170 offset:0x3400
	v_mfma_f32_32x32x16_bf16 v[18:33], v[208:211], v[38:41], v[18:33]
	ds_read_b64_tr_b16 v[64:65], v170 offset:0x3c00
	s_waitcnt lgkmcnt(0)
	v_mfma_f32_32x32x16_bf16 v[18:33], v[222:225], v[42:45], v[18:33]
	v_mfma_f32_32x32x16_bf16 v[34:49], v[50:53], v[34:37], 0
	v_mfma_f32_32x32x16_bf16 v[34:49], v[204:207], v[54:57], v[34:49]
	ds_read_b64_tr_b16 v[54:55], v170 offset:0x600
	ds_read_b64_tr_b16 v[56:57], v170 offset:0xe00
	ds_read_b64_tr_b16 v[226:227], v170 offset:0x1600
	ds_read_b64_tr_b16 v[228:229], v170 offset:0x1e00
	ds_read_b64_tr_b16 v[230:231], v170 offset:0x2600
	ds_read_b64_tr_b16 v[232:233], v170 offset:0x2e00
	ds_read_b64_tr_b16 v[234:235], v170 offset:0x3600
	v_mfma_f32_32x32x16_bf16 v[34:49], v[208:211], v[58:61], v[34:49]
	ds_read_b64_tr_b16 v[236:237], v170 offset:0x3e00
	s_waitcnt lgkmcnt(0)
	v_mfma_f32_32x32x16_bf16 v[34:49], v[222:225], v[62:65], v[34:49]
	v_mfma_f32_32x32x16_bf16 v[50:65], v[50:53], v[54:57], 0
	v_max_f32_e32 v155, v83, v83
	v_max_f32_e32 v159, v82, v82
	v_max_f32_e32 v155, v159, v155
	v_max3_f32 v155, v155, v84, v85
	v_max3_f32 v155, v155, v86, v87
	v_max3_f32 v155, v155, v88, v89
	v_max3_f32 v155, v155, v90, v91
	v_mfma_f32_32x32x16_bf16 v[50:65], v[204:207], v[226:229], v[50:65]
	v_max3_f32 v155, v155, v92, v93
	v_max3_f32 v155, v155, v94, v95
	v_max3_f32 v155, v155, v96, v97
	v_max3_f32 v155, v155, v66, v67
	v_max3_f32 v155, v155, v68, v69
	v_max3_f32 v155, v155, v70, v71
	v_max3_f32 v155, v155, v72, v73
	v_max3_f32 v155, v155, v74, v75
	v_mfma_f32_32x32x16_bf16 v[50:65], v[208:211], v[230:233], v[50:65]
	v_max3_f32 v155, v155, v76, v77
	v_max3_f32 v155, v155, v78, v79
	v_max3_f32 v155, v155, v80, v81
	v_mov_b32_e32 v159, v155
	s_nop 1
	v_permlane32_swap_b32_e32 v155, v159
	v_max_f32_e32 v159, v159, v159
	v_max_f32_e32 v155, v155, v155
	v_max_f32_e32 v155, v155, v159
	v_sub_f32_e32 v159, v155, v153
	v_max_f32_e32 v155, v153, v155
	v_mfma_f32_32x32x16_bf16 v[50:65], v[222:225], v[234:237], v[50:65]
	v_cmp_ge_f32_e32 vcc, s5, v159
	v_sub_f32_e32 v159, v153, v155
	v_mul_f32_e32 v159, 0x3dd53b94, v159
	v_exp_f32_e32 v159, v159
	s_cmp_eq_u64 vcc, exec
	s_cselect_b64 s[42:43], -1, 0
	s_barrier
	s_waitcnt vmcnt(0)
	v_cndmask_b32_e64 v221, v159, 1.0, s[42:43]
	v_cmp_gt_f32_e32 vcc, 1.0, v221
	s_waitcnt vmcnt(1)
	ds_write_b128 v214, v[148:151]
	ds_write_b128 v215, v[132:135]
	ds_write_b128 v216, v[136:139] offset:32768
	ds_write_b128 v217, v[140:143] offset:32768
	s_waitcnt vmcnt(0)
	ds_write_b128 v218, v[144:147] offset:32768
	s_cbranch_vccz .LBB0_826
	s_and_saveexec_b64 s[36:37], s[40:41]
	ds_write_b32 v175, v221 offset:128
	s_or_b64 exec, exec, s[36:37]
	s_waitcnt lgkmcnt(0)
	ds_read_b128 v[132:135], v174 offset:224
	ds_read_b128 v[136:139], v174 offset:192
	ds_read_b128 v[140:143], v174 offset:160
	ds_read_b128 v[144:147], v174 offset:128
	s_waitcnt lgkmcnt(3)
	v_pk_mul_f32 v[16:17], v[16:17], v[134:135]
	s_waitcnt lgkmcnt(2)
	v_pk_mul_f32 v[12:13], v[12:13], v[138:139]
	s_waitcnt lgkmcnt(1)
	v_pk_mul_f32 v[8:9], v[8:9], v[142:143]
	s_waitcnt lgkmcnt(0)
	v_pk_mul_f32 v[4:5], v[4:5], v[146:147]
	v_pk_mul_f32 v[14:15], v[14:15], v[132:133]
	v_pk_mul_f32 v[10:11], v[10:11], v[136:137]
	v_pk_mul_f32 v[6:7], v[6:7], v[140:141]
	v_pk_mul_f32 v[2:3], v[2:3], v[144:145]
	v_pk_mul_f32 v[32:33], v[32:33], v[134:135]
	v_pk_mul_f32 v[28:29], v[28:29], v[138:139]
	v_pk_mul_f32 v[24:25], v[24:25], v[142:143]
	v_pk_mul_f32 v[20:21], v[20:21], v[146:147]
	v_pk_mul_f32 v[30:31], v[30:31], v[132:133]
	v_pk_mul_f32 v[26:27], v[26:27], v[136:137]
	v_pk_mul_f32 v[22:23], v[22:23], v[140:141]
	v_pk_mul_f32 v[18:19], v[18:19], v[144:145]
	v_pk_mul_f32 v[48:49], v[48:49], v[134:135]
	v_pk_mul_f32 v[44:45], v[44:45], v[138:139]
	v_pk_mul_f32 v[40:41], v[40:41], v[142:143]
	v_pk_mul_f32 v[36:37], v[36:37], v[146:147]
	v_pk_mul_f32 v[46:47], v[46:47], v[132:133]
	v_pk_mul_f32 v[42:43], v[42:43], v[136:137]
	v_pk_mul_f32 v[38:39], v[38:39], v[140:141]
	v_pk_mul_f32 v[34:35], v[34:35], v[144:145]
	v_pk_mul_f32 v[64:65], v[64:65], v[134:135]
	v_pk_mul_f32 v[60:61], v[60:61], v[138:139]
	v_pk_mul_f32 v[56:57], v[56:57], v[142:143]
	v_pk_mul_f32 v[52:53], v[52:53], v[146:147]
	v_pk_mul_f32 v[62:63], v[62:63], v[132:133]
	v_pk_mul_f32 v[58:59], v[58:59], v[136:137]
	v_pk_mul_f32 v[54:55], v[54:55], v[140:141]
	v_pk_mul_f32 v[50:51], v[50:51], v[144:145]

.LBB0_855:
	s_add_i32 s11, s11, 2
	ds_read_b128 v[66:69], v183 offset:57344
	ds_read_b128 v[70:73], v226 offset:57344
	ds_read_b128 v[234:237], v184 offset:57344
	ds_read_b128 v[238:241], v225 offset:57344
	s_add_i32 m0, s100, 0x4000
	s_nop 0
	global_load_lds_dwordx4 v178, s[14:15]
	s_add_i32 m0, s100, 0x4400
	s_nop 0
	global_load_lds_dwordx4 v179, s[14:15]
	s_sub_i32 s0, s13, 64
	s_cmp_lt_u32 s11, 3
	s_cselect_b32 s0, s12, s0
	s_ashr_i32 s1, s0, 31
	s_lshl_b64 s[14:15], s[0:1], 10
	s_add_u32 s14, s9, s14
	s_addc_u32 s15, s10, s15
	s_mul_hi_i32 s1, s0, 0x600
	s_mulk_i32 s0, 0x600
	s_add_u32 s0, s2, s0
	s_addc_u32 s1, s8, s1
	s_add_i32 m0, s101, 0x8000
	s_nop 0
	global_load_lds_dwordx4 v180, s[0:1]
	s_add_i32 m0, s101, 0x8400
	s_nop 0
	global_load_lds_dwordx4 v181, s[0:1]
	s_add_i32 m0, s101, 0x8800
	s_nop 0
	global_load_lds_dwordx4 v182, s[0:1]
	v_add_f32_e32 v152, 0, v153
	v_add_f32_e32 v152, v154, v152
	s_waitcnt lgkmcnt(2)
	v_mfma_f32_32x32x16_bf16 v[82:97], v[66:69], v[128:131], 0
	v_add_f32_e32 v152, v230, v152
	v_add_f32_e32 v152, v231, v152
	v_add_f32_e32 v152, v232, v152
	v_add_f32_e32 v152, v233, v152
	v_add_f32_e32 v152, v155, v152
	v_add_f32_e32 v152, v229, v152
	v_add_f32_e32 v152, v151, v152
	v_mfma_f32_32x32x16_bf16 v[66:81], v[70:73], v[128:131], 0
	ds_read_b128 v[162:165], v185 offset:57344
	ds_read_b128 v[166:169], v224 offset:57344
	v_add_f32_e32 v152, v156, v152
	v_add_f32_e32 v152, v157, v152
	v_add_f32_e32 v152, v158, v152
	v_exp_f32_e32 v144, v144
	v_add_f32_e32 v152, v148, v152
	v_exp_f32_e32 v145, v145
	v_add_f32_e32 v152, v149, v152
	s_waitcnt lgkmcnt(2)
	v_mfma_f32_32x32x16_bf16 v[82:97], v[234:237], v[124:127], v[82:97]
	v_exp_f32_e32 v142, v142
	v_add_f32_e32 v152, v150, v152
	v_exp_f32_e32 v143, v143
	v_add_f32_e32 v152, v159, v152
	v_exp_f32_e32 v136, v136
	v_add_f32_e32 v152, v144, v152
	v_exp_f32_e32 v137, v137
	v_mfma_f32_32x32x16_bf16 v[66:81], v[238:241], v[124:127], v[66:81]
	ds_read_b128 v[234:237], v186 offset:57344
	ds_read_b128 v[238:241], v223 offset:57344
	v_add_f32_e32 v152, v145, v152
	v_exp_f32_e32 v134, v134
	v_add_f32_e32 v152, v142, v152
	v_exp_f32_e32 v135, v135
	v_add_f32_e32 v152, v143, v152
	v_exp_f32_e32 v132, v132
	s_waitcnt lgkmcnt(2)
	v_mfma_f32_32x32x16_bf16 v[82:97], v[162:165], v[120:123], v[82:97]
	v_add_f32_e32 v152, v136, v152
	v_exp_f32_e32 v133, v133
	v_add_f32_e32 v152, v137, v152
	v_exp_f32_e32 v146, v146
	v_add_f32_e32 v152, v134, v152
	v_exp_f32_e32 v147, v147
	v_add_f32_e32 v152, v135, v152
	v_mfma_f32_32x32x16_bf16 v[66:81], v[166:169], v[120:123], v[66:81]
	ds_read_b128 v[162:165], v187 offset:57344
	ds_read_b128 v[166:169], v222 offset:57344
	v_exp_f32_e32 v140, v140
	v_add_f32_e32 v152, v132, v152
	v_exp_f32_e32 v141, v141
	v_add_f32_e32 v152, v133, v152
	v_exp_f32_e32 v138, v138
	v_add_f32_e32 v152, v146, v152
	s_waitcnt lgkmcnt(2)
	v_mfma_f32_32x32x16_bf16 v[82:97], v[234:237], v[116:119], v[82:97]
	v_exp_f32_e32 v139, v139
	v_add_f32_e32 v152, v147, v152
	v_add_f32_e32 v152, v140, v152
	v_add_f32_e32 v152, v141, v152
	v_add_f32_e32 v152, v138, v152
	v_add_f32_e32 v227, v139, v152
	v_mov_b32_e32 v228, v227
	v_mfma_f32_32x32x16_bf16 v[66:81], v[238:241], v[116:119], v[66:81]
	ds_read_b128 v[234:237], v188 offset:57344
	ds_read_b128 v[238:241], v221 offset:57344
	v_cvt_pk_bf16_f32 v152, v153, v154
	v_cvt_pk_bf16_f32 v154, v232, v233
	v_permlane32_swap_b32_e32 v227, v228
	v_cvt_pk_bf16_f32 v153, v230, v231
	v_cvt_pk_bf16_f32 v155, v155, v229
	s_waitcnt lgkmcnt(2)
	v_mfma_f32_32x32x16_bf16 v[82:97], v[162:165], v[112:115], v[82:97]
	v_permlane32_swap_b32_e32 v152, v154
	v_cvt_pk_bf16_f32 v156, v151, v156
	v_cvt_pk_bf16_f32 v157, v157, v158
	v_cvt_pk_bf16_f32 v158, v148, v149
	v_cvt_pk_bf16_f32 v159, v150, v159
	v_cvt_pk_bf16_f32 v230, v144, v145
	v_mfma_f32_32x32x16_bf16 v[66:81], v[166:169], v[112:115], v[66:81]
	ds_read_b128 v[162:165], v189 offset:57344
	ds_read_b128 v[166:169], v220 offset:57344
	v_cvt_pk_bf16_f32 v231, v142, v143
	v_cvt_pk_bf16_f32 v232, v136, v137
	v_cvt_pk_bf16_f32 v233, v134, v135
	v_permlane32_swap_b32_e32 v153, v155
	v_permlane32_swap_b32_e32 v156, v158
	s_waitcnt lgkmcnt(2)
	v_mfma_f32_32x32x16_bf16 v[82:97], v[234:237], v[108:111], v[82:97]
	v_permlane32_swap_b32_e32 v157, v159
	v_permlane32_swap_b32_e32 v230, v232
	v_permlane32_swap_b32_e32 v231, v233
	v_mfma_f32_32x32x16_bf16 v[66:81], v[238:241], v[108:111], v[66:81]
	ds_read_b128 v[234:237], v190 offset:57344
	ds_read_b128 v[238:241], v219 offset:57344
	s_waitcnt lgkmcnt(2)
	v_mfma_f32_32x32x16_bf16 v[82:97], v[162:165], v[104:107], v[82:97]
	v_mfma_f32_32x32x16_bf16 v[66:81], v[166:169], v[104:107], v[66:81]
	ds_read_b128 v[162:165], v191 offset:57344
	ds_read_b128 v[166:169], v218 offset:57344
	ds_read_b128 v[242:245], v192
	s_waitcnt lgkmcnt(3)
	v_mfma_f32_32x32x16_bf16 v[82:97], v[234:237], v[100:103], v[82:97]
	v_mfma_f32_32x32x16_bf16 v[66:81], v[238:241], v[100:103], v[66:81]
	ds_read_b128 v[234:237], v194 offset:57344
	ds_read_b128 v[238:241], v217 offset:57344
	ds_read_b128 v[246:249], v176
	s_waitcnt lgkmcnt(3)
	v_mfma_f32_32x32x16_bf16 v[82:97], v[162:165], v[242:245], v[82:97]
	v_mfma_f32_32x32x16_bf16 v[66:81], v[166:169], v[242:245], v[66:81]
	ds_read_b128 v[162:165], v195 offset:57344
	ds_read_b128 v[166:169], v216 offset:57344
	ds_read_b128 v[242:245], v177
	s_waitcnt lgkmcnt(3)
	v_mfma_f32_32x32x16_bf16 v[82:97], v[234:237], v[246:249], v[82:97]
	v_mfma_f32_32x32x16_bf16 v[66:81], v[238:241], v[246:249], v[66:81]
	ds_read_b128 v[234:237], v196 offset:57344
	ds_read_b128 v[238:241], v215 offset:57344
	ds_read_b128 v[246:249], v175
	s_waitcnt lgkmcnt(3)
	v_mfma_f32_32x32x16_bf16 v[82:97], v[162:165], v[242:245], v[82:97]
	v_mfma_f32_32x32x16_bf16 v[66:81], v[166:169], v[242:245], v[66:81]
	s_waitcnt lgkmcnt(0)
	v_mfma_f32_32x32x16_bf16 v[82:97], v[234:237], v[246:249], v[82:97]
	v_cvt_pk_bf16_f32 v234, v132, v133
	v_cvt_pk_bf16_f32 v236, v140, v141
	v_cvt_pk_bf16_f32 v235, v146, v147
	v_cvt_pk_bf16_f32 v237, v138, v139
	v_permlane32_swap_b32_e32 v234, v236
	s_nop 0
	v_permlane32_swap_b32_e32 v235, v237
	v_mfma_f32_32x32x16_bf16 v[66:81], v[238:241], v[246:249], v[66:81]
	ds_read_b64_tr_b16 v[238:239], v174 offset:0
	ds_read_b64_tr_b16 v[240:241], v174 offset:0x800
	ds_read_b64_tr_b16 v[242:243], v174 offset:0x1000
	ds_read_b64_tr_b16 v[244:245], v174 offset:0x1800
	ds_read_b64_tr_b16 v[246:247], v174 offset:0x2000
	ds_read_b64_tr_b16 v[248:249], v174 offset:0x2800
	ds_read_b64_tr_b16 v[204:205], v174 offset:0x3000
	ds_read_b64_tr_b16 v[206:207], v174 offset:0x3800
	s_nop 0
	s_waitcnt lgkmcnt(6)
	v_mfma_f32_32x32x16_bf16 v[2:17], v[152:155], v[238:241], v[2:17]
	s_waitcnt lgkmcnt(4)
	v_mfma_f32_32x32x16_bf16 v[2:17], v[156:159], v[242:245], v[2:17]
	s_waitcnt lgkmcnt(2)
	v_mfma_f32_32x32x16_bf16 v[2:17], v[230:233], v[246:249], v[2:17]
	s_waitcnt lgkmcnt(0)
	v_mfma_f32_32x32x16_bf16 v[2:17], v[234:237], v[204:207], v[2:17]
	ds_read_b64_tr_b16 v[204:205], v174 offset:0x200
	ds_read_b64_tr_b16 v[206:207], v174 offset:0xa00
	ds_read_b64_tr_b16 v[238:239], v174 offset:0x1200
	ds_read_b64_tr_b16 v[240:241], v174 offset:0x1a00
	ds_read_b64_tr_b16 v[242:243], v174 offset:0x2200
	ds_read_b64_tr_b16 v[244:245], v174 offset:0x2a00
	ds_read_b64_tr_b16 v[246:247], v174 offset:0x3200
	ds_read_b64_tr_b16 v[248:249], v174 offset:0x3a00
	s_nop 0
	s_waitcnt lgkmcnt(6)
	v_mfma_f32_32x32x16_bf16 v[50:65], v[152:155], v[204:207], v[50:65]
	ds_read_b64_tr_b16 v[204:205], v174 offset:0x400
	ds_read_b64_tr_b16 v[206:207], v174 offset:0xc00
	s_waitcnt lgkmcnt(6)
	v_mfma_f32_32x32x16_bf16 v[50:65], v[156:159], v[238:241], v[50:65]
	ds_read_b64_tr_b16 v[238:239], v174 offset:0x1400
	ds_read_b64_tr_b16 v[240:241], v174 offset:0x1c00
	s_waitcnt lgkmcnt(6)
	v_mfma_f32_32x32x16_bf16 v[50:65], v[230:233], v[242:245], v[50:65]
	ds_read_b64_tr_b16 v[242:243], v174 offset:0x2400
	ds_read_b64_tr_b16 v[244:245], v174 offset:0x2c00
	s_waitcnt lgkmcnt(6)
	v_mfma_f32_32x32x16_bf16 v[50:65], v[234:237], v[246:249], v[50:65]
	ds_read_b64_tr_b16 v[246:247], v174 offset:0x3400
	ds_read_b64_tr_b16 v[248:249], v174 offset:0x3c00
	s_waitcnt lgkmcnt(6)
	v_mfma_f32_32x32x16_bf16 v[34:49], v[152:155], v[204:207], v[34:49]
	ds_read_b64_tr_b16 v[204:205], v174 offset:0x600
	ds_read_b64_tr_b16 v[206:207], v174 offset:0xe00
	s_waitcnt lgkmcnt(6)
	v_mfma_f32_32x32x16_bf16 v[34:49], v[156:159], v[238:241], v[34:49]
	ds_read_b64_tr_b16 v[238:239], v174 offset:0x1600
	ds_read_b64_tr_b16 v[240:241], v174 offset:0x1e00
	s_waitcnt lgkmcnt(6)
	v_mfma_f32_32x32x16_bf16 v[34:49], v[230:233], v[242:245], v[34:49]
	ds_read_b64_tr_b16 v[242:243], v174 offset:0x2600
	ds_read_b64_tr_b16 v[244:245], v174 offset:0x2e00
	s_waitcnt lgkmcnt(6)
	v_mfma_f32_32x32x16_bf16 v[34:49], v[234:237], v[246:249], v[34:49]
	ds_read_b64_tr_b16 v[246:247], v174 offset:0x3600
	ds_read_b64_tr_b16 v[248:249], v174 offset:0x3e00
	s_waitcnt lgkmcnt(6)
	v_mfma_f32_32x32x16_bf16 v[18:33], v[152:155], v[204:207], v[18:33]
	v_max_f32_e32 v152, v83, v83
	v_max_f32_e32 v153, v82, v82
	v_max_f32_e32 v152, v153, v152
	v_max3_f32 v152, v152, v84, v85
	v_max3_f32 v152, v152, v86, v87
	v_max3_f32 v152, v152, v88, v89
	v_max3_f32 v152, v152, v90, v91
	v_max3_f32 v152, v152, v92, v93
	v_max3_f32 v152, v152, v94, v95
	s_waitcnt lgkmcnt(4)
	v_mfma_f32_32x32x16_bf16 v[18:33], v[156:159], v[238:241], v[18:33]
	v_max3_f32 v152, v152, v96, v97
	v_max3_f32 v152, v152, v66, v67
	v_max3_f32 v152, v152, v68, v69
	v_max3_f32 v152, v152, v70, v71
	v_max3_f32 v152, v152, v72, v73
	v_max3_f32 v152, v152, v74, v75
	v_max3_f32 v152, v152, v76, v77
	v_max3_f32 v152, v152, v78, v79
	s_waitcnt lgkmcnt(2)
	v_mfma_f32_32x32x16_bf16 v[18:33], v[230:233], v[242:245], v[18:33]
	v_max3_f32 v152, v152, v80, v81
	v_mov_b32_e32 v153, v152
	s_nop 1
	v_permlane32_swap_b32_e32 v152, v153
	v_max_f32_e32 v153, v153, v153
	v_max_f32_e32 v152, v152, v152
	v_max_f32_e32 v152, v152, v153
	v_sub_f32_e32 v153, v152, v214
	v_cmp_ge_f32_e32 vcc, s5, v153
	v_max_f32_e32 v153, v214, v214
	v_max_f32_e32 v152, v153, v152
	s_waitcnt lgkmcnt(0)
	v_mfma_f32_32x32x16_bf16 v[18:33], v[234:237], v[246:249], v[18:33]
	v_sub_f32_e32 v153, v214, v152
	v_mul_f32_e32 v153, 0x3dd53b94, v153
	v_exp_f32_e32 v153, v153
	s_cmp_eq_u64 vcc, exec
	s_cselect_b64 s[40:41], -1, 0
	s_cmp_lt_u32 s100, 0x2000
	s_cbranch_scc1 .Lmy_att_e1
	s_waitcnt vmcnt(0) lgkmcnt(0)
	s_barrier

.Lmy_att_l1:
	ds_read_b128 v[66:69], v183 offset:32768
	ds_read_b128 v[70:73], v183 offset:45056
	ds_read_b128 v[204:207], v184 offset:32768
	ds_read_b128 v[236:239], v184 offset:45056
	s_add_i32 m0, s100, 0x0
	s_nop 0
	global_load_lds_dwordx4 v178, s[14:15]
	s_add_i32 m0, s100, 0x400
	s_nop 0
	global_load_lds_dwordx4 v179, s[14:15]
	s_add_i32 s0, s12, 64
	s_cmp_lt_u32 s11, 2
	s_cselect_b32 s0, s0, s13
	s_ashr_i32 s1, s0, 31
	s_lshl_b64 s[14:15], s[0:1], 10
	s_add_u32 s14, s9, s14
	s_addc_u32 s15, s10, s15
	s_mul_hi_i32 s1, s0, 0x600
	s_mulk_i32 s0, 0x600
	s_add_u32 s0, s2, s0
	s_addc_u32 s1, s8, s1
	s_add_i32 m0, s101, 0xe000
	s_nop 0
	global_load_lds_dwordx4 v180, s[0:1]
	s_add_i32 m0, s101, 0xe400
	s_nop 0
	global_load_lds_dwordx4 v181, s[0:1]
	s_add_i32 m0, s101, 0xe800
	s_nop 0
	global_load_lds_dwordx4 v182, s[0:1]
	v_exp_f32_e32 v209, v152
	v_add_f32_e32 v152, 0, v141
	s_waitcnt lgkmcnt(2)
	v_mfma_f32_32x32x16_bf16 v[82:97], v[66:69], v[128:131], 0
	v_add_f32_e32 v152, v143, v152
	v_add_f32_e32 v152, v144, v152
	v_add_f32_e32 v152, v145, v152
	v_add_f32_e32 v152, v146, v152
	v_add_f32_e32 v152, v147, v152
	v_add_f32_e32 v152, v140, v152
	v_add_f32_e32 v152, v142, v152
	v_mfma_f32_32x32x16_bf16 v[66:81], v[70:73], v[128:131], 0
	ds_read_b128 v[162:165], v185 offset:32768
	ds_read_b128 v[166:169], v185 offset:45056
	v_add_f32_e32 v152, v135, v152
	v_add_f32_e32 v152, v137, v152
	v_add_f32_e32 v152, v138, v152
	v_add_f32_e32 v152, v139, v152
	v_add_f32_e32 v152, v132, v152
	v_add_f32_e32 v152, v133, v152
	v_add_f32_e32 v152, v134, v152
	s_waitcnt lgkmcnt(2)
	v_mfma_f32_32x32x16_bf16 v[82:97], v[204:207], v[124:127], v[82:97]
	v_add_f32_e32 v152, v136, v152
	v_exp_f32_e32 v208, v230
	v_exp_f32_e32 v150, v150
	v_exp_f32_e32 v151, v151
	v_exp_f32_e32 v210, v153
	v_exp_f32_e32 v211, v154
	v_exp_f32_e32 v233, v156
	v_mfma_f32_32x32x16_bf16 v[66:81], v[236:239], v[124:127], v[66:81]
	ds_read_b128 v[204:207], v186 offset:32768
	ds_read_b128 v[236:239], v186 offset:45056
	v_exp_f32_e32 v149, v149
	v_exp_f32_e32 v148, v148
	v_cvt_pk_bf16_f32 v153, v144, v145
	v_cvt_pk_bf16_f32 v154, v146, v147
	v_cvt_pk_bf16_f32 v156, v135, v137
	v_cvt_pk_bf16_f32 v230, v210, v211
	s_waitcnt lgkmcnt(2)
	v_mfma_f32_32x32x16_bf16 v[82:97], v[162:165], v[120:123], v[82:97]
	v_mfma_f32_32x32x16_bf16 v[66:81], v[166:169], v[120:123], v[66:81]
	ds_read_b128 v[162:165], v187 offset:32768
	ds_read_b128 v[166:169], v187 offset:45056
	s_waitcnt lgkmcnt(2)
	v_mfma_f32_32x32x16_bf16 v[82:97], v[204:207], v[116:119], v[82:97]
	v_mfma_f32_32x32x16_bf16 v[66:81], v[236:239], v[116:119], v[66:81]
	ds_read_b128 v[204:207], v188 offset:32768
	ds_read_b128 v[236:239], v188 offset:45056
	s_waitcnt lgkmcnt(2)
	v_mfma_f32_32x32x16_bf16 v[82:97], v[162:165], v[112:115], v[82:97]
	v_mfma_f32_32x32x16_bf16 v[66:81], v[166:169], v[112:115], v[66:81]
	ds_read_b128 v[162:165], v189 offset:32768
	ds_read_b128 v[166:169], v189 offset:45056
	s_waitcnt lgkmcnt(2)
	v_mfma_f32_32x32x16_bf16 v[82:97], v[204:207], v[108:111], v[82:97]
	v_mfma_f32_32x32x16_bf16 v[66:81], v[236:239], v[108:111], v[66:81]
	ds_read_b128 v[204:207], v190 offset:32768
	ds_read_b128 v[236:239], v190 offset:45056
	s_waitcnt lgkmcnt(2)
	v_mfma_f32_32x32x16_bf16 v[82:97], v[162:165], v[104:107], v[82:97]
	v_mfma_f32_32x32x16_bf16 v[66:81], v[166:169], v[104:107], v[66:81]
	ds_read_b128 v[162:165], v191 offset:32768
	ds_read_b128 v[166:169], v191 offset:45056
	ds_read_b128 v[240:243], v192
	s_waitcnt lgkmcnt(3)
	v_mfma_f32_32x32x16_bf16 v[82:97], v[204:207], v[100:103], v[82:97]
	v_mfma_f32_32x32x16_bf16 v[66:81], v[236:239], v[100:103], v[66:81]
	ds_read_b128 v[204:207], v194 offset:32768
	ds_read_b128 v[236:239], v194 offset:45056
	ds_read_b128 v[244:247], v176
	s_waitcnt lgkmcnt(3)
	v_mfma_f32_32x32x16_bf16 v[82:97], v[162:165], v[240:243], v[82:97]
	v_mfma_f32_32x32x16_bf16 v[66:81], v[166:169], v[240:243], v[66:81]
	ds_read_b128 v[162:165], v195 offset:32768
	ds_read_b128 v[166:169], v195 offset:45056
	ds_read_b128 v[240:243], v177
	s_waitcnt lgkmcnt(3)
	v_mfma_f32_32x32x16_bf16 v[82:97], v[204:207], v[244:247], v[82:97]
	v_mfma_f32_32x32x16_bf16 v[66:81], v[236:239], v[244:247], v[66:81]
	ds_read_b128 v[204:207], v196 offset:32768
	ds_read_b128 v[236:239], v196 offset:45056
	ds_read_b128 v[244:247], v175
	s_waitcnt lgkmcnt(3)
	v_mfma_f32_32x32x16_bf16 v[82:97], v[162:165], v[240:243], v[82:97]
	v_mfma_f32_32x32x16_bf16 v[66:81], v[166:169], v[240:243], v[66:81]
	s_waitcnt lgkmcnt(0)
	v_mfma_f32_32x32x16_bf16 v[82:97], v[204:207], v[244:247], v[82:97]
	v_exp_f32_e32 v204, v157
	v_exp_f32_e32 v205, v158
	v_exp_f32_e32 v206, v159
	v_exp_f32_e32 v207, v229
	v_add_f32_e32 v152, v204, v152
	v_add_f32_e32 v152, v205, v152
	v_add_f32_e32 v152, v206, v152
	v_add_f32_e32 v152, v207, v152
	v_add_f32_e32 v152, v208, v152
	v_add_f32_e32 v152, v150, v152
	v_exp_f32_e32 v229, v155
	v_add_f32_e32 v152, v151, v152
	v_add_f32_e32 v152, v209, v152
	v_add_f32_e32 v152, v210, v152
	v_mfma_f32_32x32x16_bf16 v[66:81], v[236:239], v[244:247], v[66:81]
	v_exp_f32_e32 v237, v231
	v_add_f32_e32 v152, v211, v152
	v_exp_f32_e32 v238, v232
	v_add_f32_e32 v152, v229, v152
	v_add_f32_e32 v152, v233, v152
	v_add_f32_e32 v152, v149, v152
	v_add_f32_e32 v152, v237, v152
	v_add_f32_e32 v152, v238, v152
	v_add_f32_e32 v235, v148, v152
	v_mov_b32_e32 v236, v235
	v_cvt_pk_bf16_f32 v152, v141, v143
	v_cvt_pk_bf16_f32 v155, v140, v142
	v_permlane32_swap_b32_e32 v235, v236
	v_permlane32_swap_b32_e32 v152, v154
	v_permlane32_swap_b32_e32 v153, v155
	v_cvt_pk_bf16_f32 v157, v138, v139
	v_cvt_pk_bf16_f32 v158, v132, v133
	v_cvt_pk_bf16_f32 v159, v134, v136
	v_cvt_pk_bf16_f32 v204, v204, v205
	v_cvt_pk_bf16_f32 v205, v206, v207
	v_cvt_pk_bf16_f32 v206, v208, v150
	v_cvt_pk_bf16_f32 v207, v151, v209
	v_cvt_pk_bf16_f32 v231, v229, v233
	v_cvt_pk_bf16_f32 v232, v149, v237
	v_cvt_pk_bf16_f32 v233, v238, v148
	v_permlane32_swap_b32_e32 v156, v158
	v_permlane32_swap_b32_e32 v157, v159
	v_permlane32_swap_b32_e32 v204, v206
	v_permlane32_swap_b32_e32 v205, v207
	v_permlane32_swap_b32_e32 v230, v232
	v_permlane32_swap_b32_e32 v231, v233
	ds_read_b64_tr_b16 v[238:239], v199 offset:0
	ds_read_b64_tr_b16 v[240:241], v199 offset:0x800
	ds_read_b64_tr_b16 v[242:243], v199 offset:0x1000
	ds_read_b64_tr_b16 v[244:245], v199 offset:0x1800
	ds_read_b64_tr_b16 v[246:247], v199 offset:0x2000
	ds_read_b64_tr_b16 v[248:249], v199 offset:0x2800
	ds_read_b64_tr_b16 v[208:209], v199 offset:0x3000
	ds_read_b64_tr_b16 v[210:211], v199 offset:0x3800
	s_nop 0
	s_waitcnt lgkmcnt(6)
	v_mfma_f32_32x32x16_bf16 v[2:17], v[152:155], v[238:241], v[2:17]
	s_waitcnt lgkmcnt(4)
	v_mfma_f32_32x32x16_bf16 v[2:17], v[156:159], v[242:245], v[2:17]
	s_waitcnt lgkmcnt(2)
	v_mfma_f32_32x32x16_bf16 v[2:17], v[204:207], v[246:249], v[2:17]
	s_waitcnt lgkmcnt(0)
	v_mfma_f32_32x32x16_bf16 v[2:17], v[230:233], v[208:211], v[2:17]
	ds_read_b64_tr_b16 v[208:209], v199 offset:0x200
	ds_read_b64_tr_b16 v[210:211], v199 offset:0xa00
	ds_read_b64_tr_b16 v[238:239], v199 offset:0x1200
	ds_read_b64_tr_b16 v[240:241], v199 offset:0x1a00
	ds_read_b64_tr_b16 v[242:243], v199 offset:0x2200
	ds_read_b64_tr_b16 v[244:245], v199 offset:0x2a00
	ds_read_b64_tr_b16 v[246:247], v199 offset:0x3200
	ds_read_b64_tr_b16 v[248:249], v199 offset:0x3a00
	s_nop 0
	s_waitcnt lgkmcnt(6)
	v_mfma_f32_32x32x16_bf16 v[50:65], v[152:155], v[208:211], v[50:65]
	ds_read_b64_tr_b16 v[208:209], v199 offset:0x400
	ds_read_b64_tr_b16 v[210:211], v199 offset:0xc00
	s_waitcnt lgkmcnt(6)
	v_mfma_f32_32x32x16_bf16 v[50:65], v[156:159], v[238:241], v[50:65]
	ds_read_b64_tr_b16 v[238:239], v199 offset:0x1400
	ds_read_b64_tr_b16 v[240:241], v199 offset:0x1c00
	s_waitcnt lgkmcnt(6)
	v_mfma_f32_32x32x16_bf16 v[50:65], v[204:207], v[242:245], v[50:65]
	ds_read_b64_tr_b16 v[242:243], v199 offset:0x2400
	ds_read_b64_tr_b16 v[244:245], v199 offset:0x2c00
	s_waitcnt lgkmcnt(6)
	v_mfma_f32_32x32x16_bf16 v[50:65], v[230:233], v[246:249], v[50:65]
	ds_read_b64_tr_b16 v[246:247], v199 offset:0x3400
	ds_read_b64_tr_b16 v[248:249], v199 offset:0x3c00
	s_waitcnt lgkmcnt(6)
	v_mfma_f32_32x32x16_bf16 v[34:49], v[152:155], v[208:211], v[34:49]
	ds_read_b64_tr_b16 v[208:209], v199 offset:0x600
	ds_read_b64_tr_b16 v[210:211], v199 offset:0xe00
	s_waitcnt lgkmcnt(6)
	v_mfma_f32_32x32x16_bf16 v[34:49], v[156:159], v[238:241], v[34:49]
	ds_read_b64_tr_b16 v[238:239], v199 offset:0x1600
	ds_read_b64_tr_b16 v[240:241], v199 offset:0x1e00
	s_waitcnt lgkmcnt(6)
	v_mfma_f32_32x32x16_bf16 v[34:49], v[204:207], v[242:245], v[34:49]
	ds_read_b64_tr_b16 v[242:243], v199 offset:0x2600
	ds_read_b64_tr_b16 v[244:245], v199 offset:0x2e00
	s_waitcnt lgkmcnt(6)
	v_mfma_f32_32x32x16_bf16 v[34:49], v[230:233], v[246:249], v[34:49]
	ds_read_b64_tr_b16 v[246:247], v199 offset:0x3600
	ds_read_b64_tr_b16 v[248:249], v199 offset:0x3e00
	s_waitcnt lgkmcnt(6)
	v_mfma_f32_32x32x16_bf16 v[18:33], v[152:155], v[208:211], v[18:33]
	v_max_f32_e32 v152, v83, v83
	v_max_f32_e32 v153, v82, v82
	v_max_f32_e32 v152, v153, v152
	v_max3_f32 v152, v152, v84, v85
	v_max3_f32 v152, v152, v86, v87
	v_max3_f32 v152, v152, v88, v89
	v_max3_f32 v152, v152, v90, v91
	v_max3_f32 v152, v152, v92, v93
	v_max3_f32 v152, v152, v94, v95
	s_waitcnt lgkmcnt(4)
	v_mfma_f32_32x32x16_bf16 v[18:33], v[156:159], v[238:241], v[18:33]
	v_max3_f32 v152, v152, v96, v97
	v_max3_f32 v152, v152, v66, v67
	v_max3_f32 v152, v152, v68, v69
	v_max3_f32 v152, v152, v70, v71
	v_max3_f32 v152, v152, v72, v73
	v_max3_f32 v152, v152, v74, v75
	v_max3_f32 v152, v152, v76, v77
	v_max3_f32 v152, v152, v78, v79
	s_waitcnt lgkmcnt(2)
	v_mfma_f32_32x32x16_bf16 v[18:33], v[204:207], v[242:245], v[18:33]
	v_max3_f32 v152, v152, v80, v81
	v_mov_b32_e32 v153, v152
	s_nop 1
	v_permlane32_swap_b32_e32 v152, v153
	v_max_f32_e32 v153, v153, v153
	v_max_f32_e32 v152, v152, v152
	v_max_f32_e32 v152, v152, v153
	v_sub_f32_e32 v153, v152, v214
	v_cmp_ge_f32_e32 vcc, s5, v153
	v_max_f32_e32 v153, v214, v214
	v_max_f32_e32 v153, v153, v152
	s_waitcnt lgkmcnt(0)
	v_mfma_f32_32x32x16_bf16 v[18:33], v[230:233], v[246:249], v[18:33]
	v_sub_f32_e32 v152, v214, v153
	v_mul_f32_e32 v152, 0x3dd53b94, v152
	v_exp_f32_e32 v152, v152
	s_cmp_eq_u64 vcc, exec
	s_cselect_b64 s[40:41], -1, 0
	s_cmp_lt_u32 s100, 0x2000
	s_cbranch_scc1 .Lmy_att_e2
	s_waitcnt vmcnt(0) lgkmcnt(0)
	s_barrier
